# RG-LRU conv: the four per-channel FMAs done two channels at a time with v_pk_fma_f32 (same tap order), tap weights read from LDS one group ahead
# baseline (speedup 1.0000x reference)
; #define LAS __attribute__((address_space(3)))
; __device__ __forceinline__ unsigned pk2(float lo, float hi) { f32x2_t v = {lo, hi}; bf16x2_t b = __builtin_convertvector(v, bf16x2_t); return __builtin_bit_cast(unsigned, b); }
; __device__ __forceinline__ float bflo(unsigned u) { return __uint_as_float(u << 16); }
; __device__ __forceinline__ float bfhi(unsigned u) { return __uint_as_float(u & 0xffff0000u); }
; __device__ __forceinline__ void lru_phase(const Ptrs& P, LAS unsigned char* lds, int G, int wave, int lane, int tid) {
;     ...
;         float xc[5][2][4]; bf16x8 xf[5];
;         {
;           __builtin_amdgcn_sched_barrier(0);
; #pragma unroll
;           for (int s = 0; s < 5; ++s) { unsigned pkd[4];
; #pragma unroll
;               for (int half = 0; half < 2; ++half) { const int ch0 = 16 * s + 8 * half;
;                   const f32x4 cb = *(const LAS f32x4*)(par + 4 * LB + ch0 + 4 * hh);
;                   float a0 = cb[0], a1 = cb[1], a2 = cb[2], a3 = cb[3];
; #pragma unroll
;                   for (int tap = 0; tap < 4; ++tap) { const v2u rw = raw[s * 2 + half][tap];
;                       const f32x4 cw = *(const LAS f32x4*)(par + tap * LB + ch0 + 4 * hh);
;                       float c0 = cw[0], c1 = cw[1], c2 = cw[2], c3 = cw[3]; asm("" : "+v"(c0), "+v"(c1), "+v"(c2), "+v"(c3));
;                       a0 = __builtin_fmaf(c0, bflo(rw.x), a0); a1 = __builtin_fmaf(c1, bfhi(rw.x), a1); a2 = __builtin_fmaf(c2, bflo(rw.y), a2); a3 = __builtin_fmaf(c3, bfhi(rw.y), a3); }
;                   asm volatile("" : "+v"(a0), "+v"(a1), "+v"(a2), "+v"(a3));
;                   xc[s][half][0] = a0; xc[s][half][1] = a1; xc[s][half][2] = a2; xc[s][half][3] = a3;
;                   pkd[2 * half] = pk2(a0, a1); pkd[2 * half + 1] = pk2(a2, a3); __builtin_amdgcn_sched_barrier(0); }
;               v4u t = {pkd[0], pkd[1], pkd[2], pkd[3]}; xf[s] = __builtin_bit_cast(bf16x8, t); __builtin_amdgcn_sched_barrier(0); } }
.LBB0_308:
	s_ashr_i32 s35, s20, 6
	s_lshl_b32 s34, s35, 8
	s_bfe_u32 s31, s20, 0x20004
	s_add_i32 s34, s34, s26
	ds_read_b128 v[204:207], v234 offset:38144
	ds_read_b128 v[188:191], v234 offset:36864
	ds_read_b128 v[192:195], v234 offset:37184
	ds_read_b128 v[196:199], v234 offset:37504
	ds_read_b128 v[200:203], v234 offset:37824
	ds_read_b128 v[224:227], v234 offset:38176
	ds_read_b128 v[208:211], v234 offset:36896
	ds_read_b128 v[212:215], v234 offset:37216
	ds_read_b128 v[216:219], v234 offset:37536
	ds_read_b128 v[220:223], v234 offset:37856
	s_waitcnt vmcnt(33)
	v_lshlrev_b32_e32 v8, 16, v36
	v_and_b32_e32 v9, 0xffff0000, v36
	v_lshlrev_b32_e32 v10, 16, v37
	v_and_b32_e32 v11, 0xffff0000, v37
	s_waitcnt lgkmcnt(8)
	v_pk_fma_f32 v[228:229], v[188:189], v[8:9], v[204:205]
	v_pk_fma_f32 v[230:231], v[190:191], v[10:11], v[206:207]
	s_waitcnt vmcnt(23)
	v_lshlrev_b32_e32 v12, 16, v168
	v_and_b32_e32 v13, 0xffff0000, v168
	v_lshlrev_b32_e32 v14, 16, v169
	v_and_b32_e32 v15, 0xffff0000, v169
	s_waitcnt lgkmcnt(7)
	v_pk_fma_f32 v[228:229], v[192:193], v[12:13], v[228:229]
	v_pk_fma_f32 v[230:231], v[194:195], v[14:15], v[230:231]
	s_waitcnt vmcnt(13)
	v_lshlrev_b32_e32 v176, 16, v172
	v_and_b32_e32 v177, 0xffff0000, v172
	v_lshlrev_b32_e32 v178, 16, v173
	v_and_b32_e32 v179, 0xffff0000, v173
	s_waitcnt lgkmcnt(6)
	v_pk_fma_f32 v[228:229], v[196:197], v[176:177], v[228:229]
	v_pk_fma_f32 v[230:231], v[198:199], v[178:179], v[230:231]
	s_waitcnt vmcnt(3)
	v_lshlrev_b32_e32 v180, 16, v174
	v_and_b32_e32 v181, 0xffff0000, v174
	v_lshlrev_b32_e32 v182, 16, v175
	v_and_b32_e32 v183, 0xffff0000, v175
	s_waitcnt lgkmcnt(5)
	v_pk_fma_f32 v[228:229], v[200:201], v[180:181], v[228:229]
	v_pk_fma_f32 v[50:51], v[202:203], v[182:183], v[230:231]
	v_mov_b32_e32 v45, v228
	v_mov_b32_e32 v46, v229
	v_cvt_pk_bf16_f32 v36, v228, v229
	v_cvt_pk_bf16_f32 v37, v50, v51
	ds_read_b128 v[204:207], v234 offset:38208
	ds_read_b128 v[188:191], v234 offset:36928
	ds_read_b128 v[192:195], v234 offset:37248
	ds_read_b128 v[196:199], v234 offset:37568
	ds_read_b128 v[200:203], v234 offset:37888
	v_lshlrev_b32_e32 v8, 16, v38
	v_and_b32_e32 v9, 0xffff0000, v38
	v_lshlrev_b32_e32 v10, 16, v39
	v_and_b32_e32 v11, 0xffff0000, v39
	s_waitcnt lgkmcnt(8)
	v_pk_fma_f32 v[228:229], v[208:209], v[8:9], v[224:225]
	v_pk_fma_f32 v[230:231], v[210:211], v[10:11], v[226:227]
	v_lshlrev_b32_e32 v12, 16, v164
	v_and_b32_e32 v13, 0xffff0000, v164
	v_lshlrev_b32_e32 v14, 16, v165
	v_and_b32_e32 v15, 0xffff0000, v165
	s_waitcnt lgkmcnt(7)
	v_pk_fma_f32 v[228:229], v[212:213], v[12:13], v[228:229]
	v_pk_fma_f32 v[230:231], v[214:215], v[14:15], v[230:231]
	v_lshlrev_b32_e32 v176, 16, v166
	v_and_b32_e32 v177, 0xffff0000, v166
	v_lshlrev_b32_e32 v178, 16, v167
	v_and_b32_e32 v179, 0xffff0000, v167
	s_waitcnt lgkmcnt(6)
	v_pk_fma_f32 v[228:229], v[216:217], v[176:177], v[228:229]
	v_pk_fma_f32 v[230:231], v[218:219], v[178:179], v[230:231]
	s_waitcnt vmcnt(2)
	v_lshlrev_b32_e32 v180, 16, v170
	v_and_b32_e32 v181, 0xffff0000, v170
	v_lshlrev_b32_e32 v182, 16, v171
	v_and_b32_e32 v183, 0xffff0000, v171
	s_waitcnt lgkmcnt(5)
	v_pk_fma_f32 v[228:229], v[220:221], v[180:181], v[228:229]
	v_pk_fma_f32 v[58:59], v[222:223], v[182:183], v[230:231]
	v_mov_b32_e32 v53, v228
	v_mov_b32_e32 v54, v229
	v_cvt_pk_bf16_f32 v38, v228, v229
	v_cvt_pk_bf16_f32 v39, v58, v59
	ds_read_b128 v[224:227], v234 offset:38240
	ds_read_b128 v[208:211], v234 offset:36960
	ds_read_b128 v[212:215], v234 offset:37280
	ds_read_b128 v[216:219], v234 offset:37600
	ds_read_b128 v[220:223], v234 offset:37920
	v_lshlrev_b32_e32 v8, 16, v40
	v_and_b32_e32 v9, 0xffff0000, v40
	v_lshlrev_b32_e32 v10, 16, v41
	v_and_b32_e32 v11, 0xffff0000, v41
	s_waitcnt lgkmcnt(8)
	v_pk_fma_f32 v[228:229], v[188:189], v[8:9], v[204:205]
	v_pk_fma_f32 v[230:231], v[190:191], v[10:11], v[206:207]
	v_lshlrev_b32_e32 v12, 16, v156
	v_and_b32_e32 v13, 0xffff0000, v156
	v_lshlrev_b32_e32 v14, 16, v157
	v_and_b32_e32 v15, 0xffff0000, v157
	s_waitcnt lgkmcnt(7)
	v_pk_fma_f32 v[228:229], v[192:193], v[12:13], v[228:229]
	v_pk_fma_f32 v[230:231], v[194:195], v[14:15], v[230:231]
	v_lshlrev_b32_e32 v176, 16, v160
	v_and_b32_e32 v177, 0xffff0000, v160
	v_lshlrev_b32_e32 v178, 16, v161
	v_and_b32_e32 v179, 0xffff0000, v161
	s_waitcnt lgkmcnt(6)
	v_pk_fma_f32 v[228:229], v[196:197], v[176:177], v[228:229]
	v_pk_fma_f32 v[230:231], v[198:199], v[178:179], v[230:231]
	v_lshlrev_b32_e32 v180, 16, v162
	v_and_b32_e32 v181, 0xffff0000, v162
	v_lshlrev_b32_e32 v182, 16, v163
	v_and_b32_e32 v183, 0xffff0000, v163
	s_waitcnt lgkmcnt(5)
	v_pk_fma_f32 v[228:229], v[200:201], v[180:181], v[228:229]
	v_pk_fma_f32 v[66:67], v[202:203], v[182:183], v[230:231]
	v_mov_b32_e32 v61, v228
	v_mov_b32_e32 v62, v229
	v_cvt_pk_bf16_f32 v40, v228, v229
	v_cvt_pk_bf16_f32 v41, v66, v67
	ds_read_b128 v[204:207], v234 offset:38272
	ds_read_b128 v[188:191], v234 offset:36992
	ds_read_b128 v[192:195], v234 offset:37312
	ds_read_b128 v[196:199], v234 offset:37632
	ds_read_b128 v[200:203], v234 offset:37952
	v_lshlrev_b32_e32 v8, 16, v42
	v_and_b32_e32 v9, 0xffff0000, v42
	v_lshlrev_b32_e32 v10, 16, v43
	v_and_b32_e32 v11, 0xffff0000, v43
	s_waitcnt lgkmcnt(8)
	v_pk_fma_f32 v[228:229], v[208:209], v[8:9], v[224:225]
	v_pk_fma_f32 v[230:231], v[210:211], v[10:11], v[226:227]
	v_lshlrev_b32_e32 v12, 16, v150
	v_and_b32_e32 v13, 0xffff0000, v150
	v_lshlrev_b32_e32 v14, 16, v151
	v_and_b32_e32 v15, 0xffff0000, v151
	s_waitcnt lgkmcnt(7)
	v_pk_fma_f32 v[228:229], v[212:213], v[12:13], v[228:229]
	v_pk_fma_f32 v[230:231], v[214:215], v[14:15], v[230:231]
	v_lshlrev_b32_e32 v176, 16, v154
	v_and_b32_e32 v177, 0xffff0000, v154
	v_lshlrev_b32_e32 v178, 16, v155
	v_and_b32_e32 v179, 0xffff0000, v155
	s_waitcnt lgkmcnt(6)
; #define LAS __attribute__((address_space(3)))
; __device__ __forceinline__ unsigned pk2(float lo, float hi) { f32x2_t v = {lo, hi}; bf16x2_t b = __builtin_convertvector(v, bf16x2_t); return __builtin_bit_cast(unsigned, b); }
; __device__ __forceinline__ float bflo(unsigned u) { return __uint_as_float(u << 16); }
; __device__ __forceinline__ float bfhi(unsigned u) { return __uint_as_float(u & 0xffff0000u); }
; __device__ __forceinline__ void lru_phase(const Ptrs& P, LAS unsigned char* lds, int G, int wave, int lane, int tid) {
;     ...
;         float xc[5][2][4]; bf16x8 xf[5];
;         {
;           __builtin_amdgcn_sched_barrier(0);
; #pragma unroll
;           for (int s = 0; s < 5; ++s) { unsigned pkd[4];
; #pragma unroll
;               for (int half = 0; half < 2; ++half) { const int ch0 = 16 * s + 8 * half;
;                   const f32x4 cb = *(const LAS f32x4*)(par + 4 * LB + ch0 + 4 * hh);
;                   float a0 = cb[0], a1 = cb[1], a2 = cb[2], a3 = cb[3];
; #pragma unroll
;                   for (int tap = 0; tap < 4; ++tap) { const v2u rw = raw[s * 2 + half][tap];
;                       const f32x4 cw = *(const LAS f32x4*)(par + tap * LB + ch0 + 4 * hh);
;                       float c0 = cw[0], c1 = cw[1], c2 = cw[2], c3 = cw[3]; asm("" : "+v"(c0), "+v"(c1), "+v"(c2), "+v"(c3));
;                       a0 = __builtin_fmaf(c0, bflo(rw.x), a0); a1 = __builtin_fmaf(c1, bfhi(rw.x), a1); a2 = __builtin_fmaf(c2, bflo(rw.y), a2); a3 = __builtin_fmaf(c3, bfhi(rw.y), a3); }
;                   asm volatile("" : "+v"(a0), "+v"(a1), "+v"(a2), "+v"(a3));
;                   xc[s][half][0] = a0; xc[s][half][1] = a1; xc[s][half][2] = a2; xc[s][half][3] = a3;
;                   pkd[2 * half] = pk2(a0, a1); pkd[2 * half + 1] = pk2(a2, a3); __builtin_amdgcn_sched_barrier(0); }
;               v4u t = {pkd[0], pkd[1], pkd[2], pkd[3]}; xf[s] = __builtin_bit_cast(bf16x8, t); __builtin_amdgcn_sched_barrier(0); } }
	v_pk_fma_f32 v[228:229], v[216:217], v[176:177], v[228:229]
	v_pk_fma_f32 v[230:231], v[218:219], v[178:179], v[230:231]
	v_lshlrev_b32_e32 v180, 16, v158
	v_and_b32_e32 v181, 0xffff0000, v158
	v_lshlrev_b32_e32 v182, 16, v159
	v_and_b32_e32 v183, 0xffff0000, v159
	s_waitcnt lgkmcnt(5)
	v_pk_fma_f32 v[228:229], v[220:221], v[180:181], v[228:229]
	v_pk_fma_f32 v[74:75], v[222:223], v[182:183], v[230:231]
	v_mov_b32_e32 v69, v228
	v_mov_b32_e32 v70, v229
	v_cvt_pk_bf16_f32 v42, v228, v229
	v_cvt_pk_bf16_f32 v43, v74, v75
	ds_read_b128 v[224:227], v234 offset:38304
	ds_read_b128 v[208:211], v234 offset:37024
	ds_read_b128 v[212:215], v234 offset:37344
	ds_read_b128 v[216:219], v234 offset:37664
	ds_read_b128 v[220:223], v234 offset:37984
	v_lshlrev_b32_e32 v8, 16, v76
	v_and_b32_e32 v9, 0xffff0000, v76
	v_lshlrev_b32_e32 v10, 16, v77
	v_and_b32_e32 v11, 0xffff0000, v77
	s_waitcnt lgkmcnt(8)
	v_pk_fma_f32 v[228:229], v[188:189], v[8:9], v[204:205]
	v_pk_fma_f32 v[230:231], v[190:191], v[10:11], v[206:207]
	v_lshlrev_b32_e32 v12, 16, v144
	v_and_b32_e32 v13, 0xffff0000, v144
	v_lshlrev_b32_e32 v14, 16, v145
	v_and_b32_e32 v15, 0xffff0000, v145
	s_waitcnt lgkmcnt(7)
	v_pk_fma_f32 v[228:229], v[192:193], v[12:13], v[228:229]
	v_pk_fma_f32 v[230:231], v[194:195], v[14:15], v[230:231]
	v_lshlrev_b32_e32 v176, 16, v148
	v_and_b32_e32 v177, 0xffff0000, v148
	v_lshlrev_b32_e32 v178, 16, v149
	v_and_b32_e32 v179, 0xffff0000, v149
	s_waitcnt lgkmcnt(6)
	v_pk_fma_f32 v[228:229], v[196:197], v[176:177], v[228:229]
	v_pk_fma_f32 v[230:231], v[198:199], v[178:179], v[230:231]
	v_lshlrev_b32_e32 v180, 16, v152
	v_and_b32_e32 v181, 0xffff0000, v152
	v_lshlrev_b32_e32 v182, 16, v153
	v_and_b32_e32 v183, 0xffff0000, v153
	s_waitcnt lgkmcnt(5)
	v_pk_fma_f32 v[228:229], v[200:201], v[180:181], v[228:229]
	v_pk_fma_f32 v[86:87], v[202:203], v[182:183], v[230:231]
	v_mov_b32_e32 v81, v228
	v_mov_b32_e32 v82, v229
	v_cvt_pk_bf16_f32 v76, v228, v229
	v_cvt_pk_bf16_f32 v77, v86, v87
	ds_read_b128 v[204:207], v234 offset:38336
	ds_read_b128 v[188:191], v234 offset:37056
	ds_read_b128 v[192:195], v234 offset:37376
	ds_read_b128 v[196:199], v234 offset:37696
	ds_read_b128 v[200:203], v234 offset:38016
	v_lshlrev_b32_e32 v8, 16, v78
	v_and_b32_e32 v9, 0xffff0000, v78
	v_lshlrev_b32_e32 v10, 16, v79
	v_and_b32_e32 v11, 0xffff0000, v79
	s_waitcnt lgkmcnt(8)
	v_pk_fma_f32 v[228:229], v[208:209], v[8:9], v[224:225]
	v_pk_fma_f32 v[230:231], v[210:211], v[10:11], v[226:227]
	v_lshlrev_b32_e32 v12, 16, v126
	v_and_b32_e32 v13, 0xffff0000, v126
	v_lshlrev_b32_e32 v14, 16, v127
	v_and_b32_e32 v15, 0xffff0000, v127
	s_waitcnt lgkmcnt(7)
	v_pk_fma_f32 v[228:229], v[212:213], v[12:13], v[228:229]
	v_pk_fma_f32 v[230:231], v[214:215], v[14:15], v[230:231]
	v_lshlrev_b32_e32 v176, 16, v142
	v_and_b32_e32 v177, 0xffff0000, v142
	v_lshlrev_b32_e32 v178, 16, v143
	v_and_b32_e32 v179, 0xffff0000, v143
	s_waitcnt lgkmcnt(6)
	v_pk_fma_f32 v[228:229], v[216:217], v[176:177], v[228:229]
	v_pk_fma_f32 v[230:231], v[218:219], v[178:179], v[230:231]
	v_lshlrev_b32_e32 v180, 16, v146
	v_and_b32_e32 v181, 0xffff0000, v146
	v_lshlrev_b32_e32 v182, 16, v147
	v_and_b32_e32 v183, 0xffff0000, v147
	s_waitcnt lgkmcnt(5)
	v_pk_fma_f32 v[228:229], v[220:221], v[180:181], v[228:229]
	v_pk_fma_f32 v[94:95], v[222:223], v[182:183], v[230:231]
	v_mov_b32_e32 v89, v228
	v_mov_b32_e32 v90, v229
	v_cvt_pk_bf16_f32 v78, v228, v229
	v_cvt_pk_bf16_f32 v79, v94, v95
	ds_read_b128 v[224:227], v234 offset:38368
	ds_read_b128 v[208:211], v234 offset:37088
	ds_read_b128 v[212:215], v234 offset:37408
	ds_read_b128 v[216:219], v234 offset:37728
	ds_read_b128 v[220:223], v234 offset:38048
	v_lshlrev_b32_e32 v8, 16, v112
	v_and_b32_e32 v9, 0xffff0000, v112
	v_lshlrev_b32_e32 v10, 16, v113
	v_and_b32_e32 v11, 0xffff0000, v113
	s_waitcnt lgkmcnt(8)
	v_pk_fma_f32 v[228:229], v[188:189], v[8:9], v[204:205]
	v_pk_fma_f32 v[230:231], v[190:191], v[10:11], v[206:207]
	v_lshlrev_b32_e32 v12, 16, v118
	v_and_b32_e32 v13, 0xffff0000, v118
	v_lshlrev_b32_e32 v14, 16, v119
	v_and_b32_e32 v15, 0xffff0000, v119
	s_waitcnt lgkmcnt(7)
	v_pk_fma_f32 v[228:229], v[192:193], v[12:13], v[228:229]
	v_pk_fma_f32 v[230:231], v[194:195], v[14:15], v[230:231]
	v_lshlrev_b32_e32 v176, 16, v124
	v_and_b32_e32 v177, 0xffff0000, v124
	v_lshlrev_b32_e32 v178, 16, v125
	v_and_b32_e32 v179, 0xffff0000, v125
	s_waitcnt lgkmcnt(6)
	v_pk_fma_f32 v[228:229], v[196:197], v[176:177], v[228:229]
	v_pk_fma_f32 v[230:231], v[198:199], v[178:179], v[230:231]
	v_lshlrev_b32_e32 v180, 16, v140
	v_and_b32_e32 v181, 0xffff0000, v140
	v_lshlrev_b32_e32 v182, 16, v141
	v_and_b32_e32 v183, 0xffff0000, v141
	s_waitcnt lgkmcnt(5)
	v_pk_fma_f32 v[228:229], v[200:201], v[180:181], v[228:229]
	v_pk_fma_f32 v[102:103], v[202:203], v[182:183], v[230:231]
	v_mov_b32_e32 v97, v228
	v_mov_b32_e32 v98, v229
	v_cvt_pk_bf16_f32 v112, v228, v229
	v_cvt_pk_bf16_f32 v113, v102, v103
	ds_read_b128 v[204:207], v234 offset:38400
	ds_read_b128 v[188:191], v234 offset:37120
	ds_read_b128 v[192:195], v234 offset:37440
	ds_read_b128 v[196:199], v234 offset:37760
	ds_read_b128 v[200:203], v234 offset:38080
	v_lshlrev_b32_e32 v8, 16, v28
	v_and_b32_e32 v9, 0xffff0000, v28
	v_lshlrev_b32_e32 v10, 16, v29
	v_and_b32_e32 v11, 0xffff0000, v29
	s_waitcnt lgkmcnt(8)
	v_pk_fma_f32 v[228:229], v[208:209], v[8:9], v[224:225]
	v_pk_fma_f32 v[230:231], v[210:211], v[10:11], v[226:227]
	v_lshlrev_b32_e32 v12, 16, v114
	v_and_b32_e32 v13, 0xffff0000, v114
	v_lshlrev_b32_e32 v14, 16, v115
	v_and_b32_e32 v15, 0xffff0000, v115
	s_waitcnt lgkmcnt(7)
; __device__ __forceinline__ void lru_phase(const Ptrs& P, LAS unsigned char* lds, int G, int wave, int lane, int tid) {
;     ...
;         float xc[5][2][4]; bf16x8 xf[5];
;         {
;           __builtin_amdgcn_sched_barrier(0);
; #pragma unroll
;           for (int s = 0; s < 5; ++s) { unsigned pkd[4];
; #pragma unroll
;               for (int half = 0; half < 2; ++half) { const int ch0 = 16 * s + 8 * half;
;                   const f32x4 cb = *(const LAS f32x4*)(par + 4 * LB + ch0 + 4 * hh);
;                   float a0 = cb[0], a1 = cb[1], a2 = cb[2], a3 = cb[3];
; #pragma unroll
;                   for (int tap = 0; tap < 4; ++tap) { const v2u rw = raw[s * 2 + half][tap];
;                       const f32x4 cw = *(const LAS f32x4*)(par + tap * LB + ch0 + 4 * hh);
;                       float c0 = cw[0], c1 = cw[1], c2 = cw[2], c3 = cw[3]; asm("" : "+v"(c0), "+v"(c1), "+v"(c2), "+v"(c3));
;                       a0 = __builtin_fmaf(c0, bflo(rw.x), a0); a1 = __builtin_fmaf(c1, bfhi(rw.x), a1); a2 = __builtin_fmaf(c2, bflo(rw.y), a2); a3 = __builtin_fmaf(c3, bfhi(rw.y), a3); }
;                   asm volatile("" : "+v"(a0), "+v"(a1), "+v"(a2), "+v"(a3));
;                   xc[s][half][0] = a0; xc[s][half][1] = a1; xc[s][half][2] = a2; xc[s][half][3] = a3;
;                   pkd[2 * half] = pk2(a0, a1); pkd[2 * half + 1] = pk2(a2, a3); __builtin_amdgcn_sched_barrier(0); }
;               v4u t = {pkd[0], pkd[1], pkd[2], pkd[3]}; xf[s] = __builtin_bit_cast(bf16x8, t); __builtin_amdgcn_sched_barrier(0); } }
;     ...
;         for (int mt = 0; mt < 3; ++mt) {
;             f32x16 gr, gi;
; #pragma unroll
;             for (int i = 0; i < 16; ++i) { gr[i] = 0.f; gi[i] = 0.f; }
;             const LAS bf16x8* wa = (const LAS bf16x8*)(lds + L_WGF) + (size_t)(mt * 6) * 64 + lane;
;             const LAS bf16x8* wb = (const LAS bf16x8*)(lds + L_WGF) + (size_t)((3 + mt) * 6) * 64 + lane;
; #pragma unroll
;             for (int s = 0; s < 5; ++s) { gr = MFMA32(wa[s * 64], xf[s], gr); gi = MFMA32(wb[s * 64], xf[s], gi); }
;             gr = MFMA32(wa[5 * 64], xone, gr); gi = MFMA32(wb[5 * 64], xone, gi);
;             __builtin_amdgcn_sched_barrier(0);
; #pragma unroll
;             for (int i4 = 0; i4 < 4; ++i4) { if (mt == 2 && i4 >= 2) continue;
;                 const int s = 2 * mt + (i4 >> 1), half = i4 & 1, ch0 = 16 * s + 8 * half + 4 * hh;
	v_pk_fma_f32 v[228:229], v[212:213], v[12:13], v[228:229]
	v_pk_fma_f32 v[230:231], v[214:215], v[14:15], v[230:231]
	v_lshlrev_b32_e32 v176, 16, v116
	v_and_b32_e32 v177, 0xffff0000, v116
	v_lshlrev_b32_e32 v178, 16, v117
	v_and_b32_e32 v179, 0xffff0000, v117
	s_waitcnt lgkmcnt(6)
	v_pk_fma_f32 v[228:229], v[216:217], v[176:177], v[228:229]
	v_pk_fma_f32 v[230:231], v[218:219], v[178:179], v[230:231]
	v_lshlrev_b32_e32 v180, 16, v122
	v_and_b32_e32 v181, 0xffff0000, v122
	v_lshlrev_b32_e32 v182, 16, v123
	v_and_b32_e32 v183, 0xffff0000, v123
	s_waitcnt lgkmcnt(5)
	v_pk_fma_f32 v[228:229], v[220:221], v[180:181], v[228:229]
	v_pk_fma_f32 v[110:111], v[222:223], v[182:183], v[230:231]
	v_mov_b32_e32 v105, v228
	v_mov_b32_e32 v106, v229
	v_cvt_pk_bf16_f32 v114, v228, v229
	v_cvt_pk_bf16_f32 v115, v110, v111
	ds_read_b128 v[224:227], v234 offset:38432
	ds_read_b128 v[208:211], v234 offset:37152
	ds_read_b128 v[212:215], v234 offset:37472
	ds_read_b128 v[216:219], v234 offset:37792
	ds_read_b128 v[220:223], v234 offset:38112
	v_lshlrev_b32_e32 v8, 16, v20
	v_and_b32_e32 v9, 0xffff0000, v20
	v_lshlrev_b32_e32 v10, 16, v21
	v_and_b32_e32 v11, 0xffff0000, v21
	s_waitcnt lgkmcnt(8)
	v_pk_fma_f32 v[228:229], v[188:189], v[8:9], v[204:205]
	v_pk_fma_f32 v[230:231], v[190:191], v[10:11], v[206:207]
	v_lshlrev_b32_e32 v12, 16, v24
	v_and_b32_e32 v13, 0xffff0000, v24
	v_lshlrev_b32_e32 v14, 16, v25
	v_and_b32_e32 v15, 0xffff0000, v25
	s_waitcnt lgkmcnt(7)
	v_pk_fma_f32 v[228:229], v[192:193], v[12:13], v[228:229]
	v_pk_fma_f32 v[230:231], v[194:195], v[14:15], v[230:231]
	v_lshlrev_b32_e32 v176, 16, v30
	v_and_b32_e32 v177, 0xffff0000, v30
	v_lshlrev_b32_e32 v178, 16, v31
	v_and_b32_e32 v179, 0xffff0000, v31
	s_waitcnt lgkmcnt(6)
	v_pk_fma_f32 v[228:229], v[196:197], v[176:177], v[228:229]
	v_pk_fma_f32 v[230:231], v[198:199], v[178:179], v[230:231]
	s_waitcnt vmcnt(1)
	v_lshlrev_b32_e32 v180, 16, v120
	v_and_b32_e32 v181, 0xffff0000, v120
	v_lshlrev_b32_e32 v182, 16, v121
	v_and_b32_e32 v183, 0xffff0000, v121
	s_waitcnt lgkmcnt(5)
	v_pk_fma_f32 v[228:229], v[200:201], v[180:181], v[228:229]
	v_pk_fma_f32 v[230:231], v[202:203], v[182:183], v[230:231]
	v_mov_b32_e32 v136, v228
	v_mov_b32_e32 v129, v229
	v_mov_b32_e32 v116, v230
	v_mov_b32_e32 v119, v231
	v_cvt_pk_bf16_f32 v124, v228, v229
	v_cvt_pk_bf16_f32 v125, v230, v231
	v_lshlrev_b32_e32 v8, 16, v16
	v_and_b32_e32 v9, 0xffff0000, v16
	v_lshlrev_b32_e32 v10, 16, v17
	v_and_b32_e32 v11, 0xffff0000, v17
	s_waitcnt lgkmcnt(3)
	v_pk_fma_f32 v[228:229], v[208:209], v[8:9], v[224:225]
	v_pk_fma_f32 v[230:231], v[210:211], v[10:11], v[226:227]
	v_lshlrev_b32_e32 v12, 16, v18
	v_and_b32_e32 v13, 0xffff0000, v18
	v_lshlrev_b32_e32 v14, 16, v19
	v_and_b32_e32 v15, 0xffff0000, v19
	s_waitcnt lgkmcnt(2)
	v_pk_fma_f32 v[228:229], v[212:213], v[12:13], v[228:229]
	v_pk_fma_f32 v[230:231], v[214:215], v[14:15], v[230:231]
	v_lshlrev_b32_e32 v176, 16, v22
	v_and_b32_e32 v177, 0xffff0000, v22
	v_lshlrev_b32_e32 v178, 16, v23
	v_and_b32_e32 v179, 0xffff0000, v23
	s_waitcnt lgkmcnt(1)
	v_pk_fma_f32 v[228:229], v[216:217], v[176:177], v[228:229]
	v_pk_fma_f32 v[230:231], v[218:219], v[178:179], v[230:231]
	s_waitcnt vmcnt(0)
	v_lshlrev_b32_e32 v180, 16, v26
	v_and_b32_e32 v181, 0xffff0000, v26
	v_lshlrev_b32_e32 v182, 16, v27
	v_and_b32_e32 v183, 0xffff0000, v27
	s_waitcnt lgkmcnt(0)
	v_pk_fma_f32 v[228:229], v[220:221], v[180:181], v[228:229]
	v_pk_fma_f32 v[230:231], v[222:223], v[182:183], v[230:231]
	v_mov_b32_e32 v120, v228
	v_mov_b32_e32 v118, v229
	v_mov_b32_e32 v117, v230
	v_mov_b32_e32 v123, v231
	v_cvt_pk_bf16_f32 v126, v228, v229
	v_cvt_pk_bf16_f32 v127, v230, v231
	ds_read_b128 v[0:3], v237
	ds_read_b128 v[140:143], v237 offset:1024
	ds_read_b128 v[16:19], v237 offset:18432
	ds_read_b128 v[144:147], v237 offset:19456
	s_waitcnt lgkmcnt(3)
	v_mfma_f32_32x32x16_bf16 v[0:15], v[0:3], v[36:39], 0
	s_waitcnt lgkmcnt(1)
	v_mfma_f32_32x32x16_bf16 v[16:31], v[16:19], v[36:39], 0
	v_mfma_f32_32x32x16_bf16 v[0:15], v[140:143], v[40:43], v[0:15]
	s_waitcnt lgkmcnt(0)
	v_mfma_f32_32x32x16_bf16 v[16:31], v[144:147], v[40:43], v[16:31]
	ds_read_b128 v[140:143], v237 offset:2048
	ds_read_b128 v[144:147], v237 offset:3072
	s_waitcnt lgkmcnt(1)
	v_mfma_f32_32x32x16_bf16 v[0:15], v[140:143], v[76:79], v[0:15]
	ds_read_b128 v[140:143], v237 offset:20480
	ds_read_b128 v[148:151], v237 offset:21504
	s_waitcnt lgkmcnt(1)
	v_mfma_f32_32x32x16_bf16 v[16:31], v[140:143], v[76:79], v[16:31]
	v_mfma_f32_32x32x16_bf16 v[0:15], v[144:147], v[112:115], v[0:15]
	ds_read_b128 v[140:143], v237 offset:4096
	ds_read_b128 v[144:147], v237 offset:5120
	s_waitcnt lgkmcnt(2)
	v_mfma_f32_32x32x16_bf16 v[16:31], v[148:151], v[112:115], v[16:31]
	s_waitcnt lgkmcnt(1)
	v_mfma_f32_32x32x16_bf16 v[0:15], v[140:143], v[124:127], v[0:15]
	ds_read_b128 v[140:143], v237 offset:22528
	ds_read_b128 v[148:151], v237 offset:23552
	s_waitcnt lgkmcnt(1)
	v_mfma_f32_32x32x16_bf16 v[16:31], v[140:143], v[124:127], v[16:31]
	v_mfma_f32_32x32x16_bf16 v[0:15], v[144:147], v[32:35], v[0:15]
	s_waitcnt lgkmcnt(0)
	v_mfma_f32_32x32x16_bf16 v[16:31], v[148:151], v[32:35], v[16:31]
	s_nop 9
	ds_read_b128 v[140:143], v234 offset:39104
	v_exp_f32_e32 v0, v0
	v_exp_f32_e32 v1, v1
	v_exp_f32_e32 v2, v2
	v_exp_f32_e32 v3, v3
	v_exp_f32_e32 v16, v16
	v_exp_f32_e32 v17, v17
	v_exp_f32_e32 v18, v18
	v_exp_f32_e32 v19, v19
	v_pk_add_f32 v[0:1], v[0:1], v[240:241] op_sel_hi:[1,0]
	v_pk_add_f32 v[2:3], v[2:3], v[240:241] op_sel_hi:[1,0]
	v_pk_add_f32 v[16:17], v[16:17], v[240:241] op_sel_hi:[1,0]
	v_pk_add_f32 v[18:19], v[18:19], v[240:241] op_sel_hi:[1,0]
	v_rcp_f32_e32 v0, v0
	v_rcp_f32_e32 v1, v1
	v_rcp_f32_e32 v2, v2
	v_rcp_f32_e32 v3, v3
	v_rcp_f32_e32 v16, v16
	v_rcp_f32_e32 v17, v17
	v_rcp_f32_e32 v18, v18
	v_rcp_f32_e32 v19, v19
	v_mul_f32_e32 v200, v45, v16
	v_mul_f32_e32 v201, v46, v17
	v_mul_f32_e32 v202, v50, v18
	v_mul_f32_e32 v203, v51, v19
	s_waitcnt lgkmcnt(0)
; #define LAS __attribute__((address_space(3)))
; __device__ __forceinline__ float ex2(float x) { return __builtin_amdgcn_exp2f(x); }
; __device__ __forceinline__ float rcpf_(float x) { return __builtin_amdgcn_rcpf(x); }
; __device__ __forceinline__ void lru_phase(const Ptrs& P, LAS unsigned char* lds, int G, int wave, int lane, int tid) {
;     ...
; #pragma unroll
;             for (int i4 = 0; i4 < 4; ++i4) { if (mt == 2 && i4 >= 2) continue;
;                 const int s = 2 * mt + (i4 >> 1), half = i4 & 1, ch0 = 16 * s + 8 * half + 4 * hh;
;                 const f32x4 ls2 = *(const LAS f32x4*)(par + 7 * LB + ch0);
;                 float A4[4], B4[4];
; #pragma unroll
;                 for (int q = 0; q < 4; ++q) { const int i = 4 * i4 + q;
;                     const float rg = rcpf_(1.0f + ex2(gr[i])), ig = rcpf_(1.0f + ex2(gi[i]));
;                     const float la2 = ls2[q] * rg, a = ex2(la2), xx = (2.0f * LN2) * la2;
;                     const float poly = -xx * (1.0f + xx * (0.5f + xx * ((1.0f / 6.0f) + xx * ((1.0f / 24.0f) + xx * (1.0f / 120.0f)))));
;                     const float om = (xx > -0.25f) ? poly : (1.0f - a * a);
;                     A4[q] = a; B4[q] = __builtin_amdgcn_sqrtf(om) * (ig * xc[s][half][q]); }
;                 asm volatile("s_nop 1\n\t"
;                     LRU_DPP4("row_shr:1 row_mask:0xf bank_mask:0xf") LRU_DPP4("row_shr:2 row_mask:0xf bank_mask:0xf") LRU_DPP4("row_shr:4 row_mask:0xf bank_mask:0xf")
;                     LRU_DPP4("row_shr:8 row_mask:0xf bank_mask:0xf") LRU_DPP4("row_bcast:15 row_mask:0xa bank_mask:0xf")
;                     : "+v"(A4[0]), "+v"(A4[1]), "+v"(A4[2]), "+v"(A4[3]), "+v"(B4[0]), "+v"(B4[1]), "+v"(B4[2]), "+v"(B4[3]));
; #pragma unroll
;                 for (int q = 0; q < 4; ++q) { Av[s][half][q] = A4[q]; xc[s][half][q] = B4[q]; }
;                 __builtin_amdgcn_sched_barrier(0); }
	v_pk_mul_f32 v[0:1], v[0:1], v[140:141]
	v_pk_mul_f32 v[2:3], v[2:3], v[142:143]
	v_pk_mul_f32 v[204:205], v[0:1], v[242:243] op_sel_hi:[1,0]
	v_pk_mul_f32 v[206:207], v[2:3], v[242:243] op_sel_hi:[1,0]
	v_exp_f32_e32 v44, v0
	v_exp_f32_e32 v45, v1
	v_exp_f32_e32 v46, v2
	v_exp_f32_e32 v47, v3
	v_pk_fma_f32 v[208:209], v[204:205], v[244:245], v[238:239] op_sel_hi:[1,0,0]
	v_pk_fma_f32 v[210:211], v[206:207], v[244:245], v[238:239] op_sel_hi:[1,0,0]
	v_pk_fma_f32 v[208:209], v[204:205], v[208:209], v[246:247] op_sel_hi:[1,1,0]
	v_pk_fma_f32 v[210:211], v[206:207], v[210:211], v[246:247] op_sel_hi:[1,1,0]
	v_pk_fma_f32 v[208:209], v[204:205], v[208:209], v[248:249] op_sel_hi:[1,1,0]
	v_pk_fma_f32 v[210:211], v[206:207], v[210:211], v[248:249] op_sel_hi:[1,1,0]
	v_pk_fma_f32 v[208:209], v[204:205], v[208:209], v[240:241] op_sel_hi:[1,1,0]
	v_pk_fma_f32 v[210:211], v[206:207], v[210:211], v[240:241] op_sel_hi:[1,1,0]
	v_pk_mul_f32 v[208:209], v[208:209], v[204:205] neg_lo:[0,1] neg_hi:[0,1]
	v_pk_mul_f32 v[210:211], v[210:211], v[206:207] neg_lo:[0,1] neg_hi:[0,1]
	v_pk_fma_f32 v[212:213], v[44:45], v[44:45], v[240:241] op_sel_hi:[1,1,0] neg_lo:[1,0,0] neg_hi:[1,0,0]
	v_pk_fma_f32 v[214:215], v[46:47], v[46:47], v[240:241] op_sel_hi:[1,1,0] neg_lo:[1,0,0] neg_hi:[1,0,0]
	v_cmp_lt_f32_e64 s[70:71], s29, v204
	v_cmp_lt_f32_e64 s[72:73], s29, v205
	v_cmp_lt_f32_e64 s[74:75], s29, v206
	v_cmp_lt_f32_e64 s[76:77], s29, v207
	v_cndmask_b32_e64 v212, v212, v208, s[70:71]
	v_cndmask_b32_e64 v213, v213, v209, s[72:73]
	v_cndmask_b32_e64 v214, v214, v210, s[74:75]
	v_cndmask_b32_e64 v215, v215, v211, s[76:77]
	v_sqrt_f32_e32 v212, v212
	v_sqrt_f32_e32 v213, v213
	v_sqrt_f32_e32 v214, v214
	v_sqrt_f32_e32 v215, v215
	v_pk_mul_f32 v[48:49], v[200:201], v[212:213]
	v_pk_mul_f32 v[50:51], v[202:203], v[214:215]
	s_nop 1
	v_fmac_f32_dpp v48, v48, v44 row_shr:1 row_mask:0xf bank_mask:0xf
	v_fmac_f32_dpp v49, v49, v45 row_shr:1 row_mask:0xf bank_mask:0xf
	v_fmac_f32_dpp v50, v50, v46 row_shr:1 row_mask:0xf bank_mask:0xf
	v_fmac_f32_dpp v51, v51, v47 row_shr:1 row_mask:0xf bank_mask:0xf
	v_mul_f32_dpp v44, v44, v44 row_shr:1 row_mask:0xf bank_mask:0xf
	v_mul_f32_dpp v45, v45, v45 row_shr:1 row_mask:0xf bank_mask:0xf
	v_mul_f32_dpp v46, v46, v46 row_shr:1 row_mask:0xf bank_mask:0xf
	v_mul_f32_dpp v47, v47, v47 row_shr:1 row_mask:0xf bank_mask:0xf
	v_fmac_f32_dpp v48, v48, v44 row_shr:2 row_mask:0xf bank_mask:0xf
	v_fmac_f32_dpp v49, v49, v45 row_shr:2 row_mask:0xf bank_mask:0xf
	v_fmac_f32_dpp v50, v50, v46 row_shr:2 row_mask:0xf bank_mask:0xf
	v_fmac_f32_dpp v51, v51, v47 row_shr:2 row_mask:0xf bank_mask:0xf
	v_mul_f32_dpp v44, v44, v44 row_shr:2 row_mask:0xf bank_mask:0xf
	v_mul_f32_dpp v45, v45, v45 row_shr:2 row_mask:0xf bank_mask:0xf
	v_mul_f32_dpp v46, v46, v46 row_shr:2 row_mask:0xf bank_mask:0xf
	v_mul_f32_dpp v47, v47, v47 row_shr:2 row_mask:0xf bank_mask:0xf
	v_fmac_f32_dpp v48, v48, v44 row_shr:4 row_mask:0xf bank_mask:0xf
	v_fmac_f32_dpp v49, v49, v45 row_shr:4 row_mask:0xf bank_mask:0xf
	v_fmac_f32_dpp v50, v50, v46 row_shr:4 row_mask:0xf bank_mask:0xf
	v_fmac_f32_dpp v51, v51, v47 row_shr:4 row_mask:0xf bank_mask:0xf
	v_mul_f32_dpp v44, v44, v44 row_shr:4 row_mask:0xf bank_mask:0xf
	v_mul_f32_dpp v45, v45, v45 row_shr:4 row_mask:0xf bank_mask:0xf
	v_mul_f32_dpp v46, v46, v46 row_shr:4 row_mask:0xf bank_mask:0xf
	v_mul_f32_dpp v47, v47, v47 row_shr:4 row_mask:0xf bank_mask:0xf
	v_fmac_f32_dpp v48, v48, v44 row_shr:8 row_mask:0xf bank_mask:0xf
	v_fmac_f32_dpp v49, v49, v45 row_shr:8 row_mask:0xf bank_mask:0xf
	v_fmac_f32_dpp v50, v50, v46 row_shr:8 row_mask:0xf bank_mask:0xf
	v_fmac_f32_dpp v51, v51, v47 row_shr:8 row_mask:0xf bank_mask:0xf
	v_mul_f32_dpp v44, v44, v44 row_shr:8 row_mask:0xf bank_mask:0xf
	v_mul_f32_dpp v45, v45, v45 row_shr:8 row_mask:0xf bank_mask:0xf
	v_mul_f32_dpp v46, v46, v46 row_shr:8 row_mask:0xf bank_mask:0xf
	v_mul_f32_dpp v47, v47, v47 row_shr:8 row_mask:0xf bank_mask:0xf
	v_fmac_f32_dpp v48, v48, v44 row_bcast:15 row_mask:0xa bank_mask:0xf
	v_fmac_f32_dpp v49, v49, v45 row_bcast:15 row_mask:0xa bank_mask:0xf
	v_fmac_f32_dpp v50, v50, v46 row_bcast:15 row_mask:0xa bank_mask:0xf
	v_fmac_f32_dpp v51, v51, v47 row_bcast:15 row_mask:0xa bank_mask:0xf
	v_mul_f32_dpp v44, v44, v44 row_bcast:15 row_mask:0xa bank_mask:0xf
	v_mul_f32_dpp v45, v45, v45 row_bcast:15 row_mask:0xa bank_mask:0xf
	v_mul_f32_dpp v46, v46, v46 row_bcast:15 row_mask:0xa bank_mask:0xf
	v_mul_f32_dpp v47, v47, v47 row_bcast:15 row_mask:0xa bank_mask:0xf
	ds_read_b128 v[0:3], v234 offset:39136
	v_exp_f32_e32 v4, v4
	v_exp_f32_e32 v5, v5
	v_exp_f32_e32 v6, v6
	v_exp_f32_e32 v7, v7
	v_exp_f32_e32 v20, v20
	v_exp_f32_e32 v21, v21
	v_exp_f32_e32 v22, v22
	v_exp_f32_e32 v23, v23
	v_pk_add_f32 v[4:5], v[4:5], v[240:241] op_sel_hi:[1,0]
	v_pk_add_f32 v[6:7], v[6:7], v[240:241] op_sel_hi:[1,0]
	v_pk_add_f32 v[20:21], v[20:21], v[240:241] op_sel_hi:[1,0]
	v_pk_add_f32 v[22:23], v[22:23], v[240:241] op_sel_hi:[1,0]
	v_rcp_f32_e32 v4, v4
	v_rcp_f32_e32 v5, v5
	v_rcp_f32_e32 v6, v6
	v_rcp_f32_e32 v7, v7
	v_rcp_f32_e32 v20, v20
	v_rcp_f32_e32 v21, v21
	v_rcp_f32_e32 v22, v22
	v_rcp_f32_e32 v23, v23
	v_mul_f32_e32 v200, v53, v20
	v_mul_f32_e32 v201, v54, v21
	v_mul_f32_e32 v202, v58, v22
	v_mul_f32_e32 v203, v59, v23
	s_waitcnt lgkmcnt(0)
; #define LAS __attribute__((address_space(3)))
; __device__ __forceinline__ float ex2(float x) { return __builtin_amdgcn_exp2f(x); }
; __device__ __forceinline__ float rcpf_(float x) { return __builtin_amdgcn_rcpf(x); }
; __device__ __forceinline__ void lru_phase(const Ptrs& P, LAS unsigned char* lds, int G, int wave, int lane, int tid) {
;     ...
; #pragma unroll
;             for (int i4 = 0; i4 < 4; ++i4) { if (mt == 2 && i4 >= 2) continue;
;                 const int s = 2 * mt + (i4 >> 1), half = i4 & 1, ch0 = 16 * s + 8 * half + 4 * hh;
;                 const f32x4 ls2 = *(const LAS f32x4*)(par + 7 * LB + ch0);
;                 float A4[4], B4[4];
; #pragma unroll
;                 for (int q = 0; q < 4; ++q) { const int i = 4 * i4 + q;
;                     const float rg = rcpf_(1.0f + ex2(gr[i])), ig = rcpf_(1.0f + ex2(gi[i]));
;                     const float la2 = ls2[q] * rg, a = ex2(la2), xx = (2.0f * LN2) * la2;
;                     const float poly = -xx * (1.0f + xx * (0.5f + xx * ((1.0f / 6.0f) + xx * ((1.0f / 24.0f) + xx * (1.0f / 120.0f)))));
;                     const float om = (xx > -0.25f) ? poly : (1.0f - a * a);
;                     A4[q] = a; B4[q] = __builtin_amdgcn_sqrtf(om) * (ig * xc[s][half][q]); }
;                 asm volatile("s_nop 1\n\t"
;                     LRU_DPP4("row_shr:1 row_mask:0xf bank_mask:0xf") LRU_DPP4("row_shr:2 row_mask:0xf bank_mask:0xf") LRU_DPP4("row_shr:4 row_mask:0xf bank_mask:0xf")
;                     LRU_DPP4("row_shr:8 row_mask:0xf bank_mask:0xf") LRU_DPP4("row_bcast:15 row_mask:0xa bank_mask:0xf")
;                     : "+v"(A4[0]), "+v"(A4[1]), "+v"(A4[2]), "+v"(A4[3]), "+v"(B4[0]), "+v"(B4[1]), "+v"(B4[2]), "+v"(B4[3]));
; #pragma unroll
;                 for (int q = 0; q < 4; ++q) { Av[s][half][q] = A4[q]; xc[s][half][q] = B4[q]; }
;                 __builtin_amdgcn_sched_barrier(0); }
	v_pk_mul_f32 v[4:5], v[4:5], v[0:1]
	v_pk_mul_f32 v[6:7], v[6:7], v[2:3]
	v_pk_mul_f32 v[204:205], v[4:5], v[242:243] op_sel_hi:[1,0]
	v_pk_mul_f32 v[206:207], v[6:7], v[242:243] op_sel_hi:[1,0]
	v_exp_f32_e32 v52, v4
	v_exp_f32_e32 v53, v5
	v_exp_f32_e32 v54, v6
	v_exp_f32_e32 v55, v7
	v_pk_fma_f32 v[208:209], v[204:205], v[244:245], v[238:239] op_sel_hi:[1,0,0]
	v_pk_fma_f32 v[210:211], v[206:207], v[244:245], v[238:239] op_sel_hi:[1,0,0]
	v_pk_fma_f32 v[208:209], v[204:205], v[208:209], v[246:247] op_sel_hi:[1,1,0]
	v_pk_fma_f32 v[210:211], v[206:207], v[210:211], v[246:247] op_sel_hi:[1,1,0]
	v_pk_fma_f32 v[208:209], v[204:205], v[208:209], v[248:249] op_sel_hi:[1,1,0]
	v_pk_fma_f32 v[210:211], v[206:207], v[210:211], v[248:249] op_sel_hi:[1,1,0]
	v_pk_fma_f32 v[208:209], v[204:205], v[208:209], v[240:241] op_sel_hi:[1,1,0]
	v_pk_fma_f32 v[210:211], v[206:207], v[210:211], v[240:241] op_sel_hi:[1,1,0]
	v_pk_mul_f32 v[208:209], v[208:209], v[204:205] neg_lo:[0,1] neg_hi:[0,1]
	v_pk_mul_f32 v[210:211], v[210:211], v[206:207] neg_lo:[0,1] neg_hi:[0,1]
	v_pk_fma_f32 v[212:213], v[52:53], v[52:53], v[240:241] op_sel_hi:[1,1,0] neg_lo:[1,0,0] neg_hi:[1,0,0]
	v_pk_fma_f32 v[214:215], v[54:55], v[54:55], v[240:241] op_sel_hi:[1,1,0] neg_lo:[1,0,0] neg_hi:[1,0,0]
	v_cmp_lt_f32_e64 s[70:71], s29, v204
	v_cmp_lt_f32_e64 s[72:73], s29, v205
	v_cmp_lt_f32_e64 s[74:75], s29, v206
	v_cmp_lt_f32_e64 s[76:77], s29, v207
	v_cndmask_b32_e64 v212, v212, v208, s[70:71]
	v_cndmask_b32_e64 v213, v213, v209, s[72:73]
	v_cndmask_b32_e64 v214, v214, v210, s[74:75]
	v_cndmask_b32_e64 v215, v215, v211, s[76:77]
	v_sqrt_f32_e32 v212, v212
	v_sqrt_f32_e32 v213, v213
	v_sqrt_f32_e32 v214, v214
	v_sqrt_f32_e32 v215, v215
	v_pk_mul_f32 v[56:57], v[200:201], v[212:213]
	v_pk_mul_f32 v[58:59], v[202:203], v[214:215]
	s_nop 1
	v_fmac_f32_dpp v56, v56, v52 row_shr:1 row_mask:0xf bank_mask:0xf
	v_fmac_f32_dpp v57, v57, v53 row_shr:1 row_mask:0xf bank_mask:0xf
	v_fmac_f32_dpp v58, v58, v54 row_shr:1 row_mask:0xf bank_mask:0xf
	v_fmac_f32_dpp v59, v59, v55 row_shr:1 row_mask:0xf bank_mask:0xf
	v_mul_f32_dpp v52, v52, v52 row_shr:1 row_mask:0xf bank_mask:0xf
	v_mul_f32_dpp v53, v53, v53 row_shr:1 row_mask:0xf bank_mask:0xf
	v_mul_f32_dpp v54, v54, v54 row_shr:1 row_mask:0xf bank_mask:0xf
	v_mul_f32_dpp v55, v55, v55 row_shr:1 row_mask:0xf bank_mask:0xf
	v_fmac_f32_dpp v56, v56, v52 row_shr:2 row_mask:0xf bank_mask:0xf
	v_fmac_f32_dpp v57, v57, v53 row_shr:2 row_mask:0xf bank_mask:0xf
	v_fmac_f32_dpp v58, v58, v54 row_shr:2 row_mask:0xf bank_mask:0xf
	v_fmac_f32_dpp v59, v59, v55 row_shr:2 row_mask:0xf bank_mask:0xf
	v_mul_f32_dpp v52, v52, v52 row_shr:2 row_mask:0xf bank_mask:0xf
	v_mul_f32_dpp v53, v53, v53 row_shr:2 row_mask:0xf bank_mask:0xf
	v_mul_f32_dpp v54, v54, v54 row_shr:2 row_mask:0xf bank_mask:0xf
	v_mul_f32_dpp v55, v55, v55 row_shr:2 row_mask:0xf bank_mask:0xf
	v_fmac_f32_dpp v56, v56, v52 row_shr:4 row_mask:0xf bank_mask:0xf
	v_fmac_f32_dpp v57, v57, v53 row_shr:4 row_mask:0xf bank_mask:0xf
	v_fmac_f32_dpp v58, v58, v54 row_shr:4 row_mask:0xf bank_mask:0xf
	v_fmac_f32_dpp v59, v59, v55 row_shr:4 row_mask:0xf bank_mask:0xf
	v_mul_f32_dpp v52, v52, v52 row_shr:4 row_mask:0xf bank_mask:0xf
	v_mul_f32_dpp v53, v53, v53 row_shr:4 row_mask:0xf bank_mask:0xf
	v_mul_f32_dpp v54, v54, v54 row_shr:4 row_mask:0xf bank_mask:0xf
	v_mul_f32_dpp v55, v55, v55 row_shr:4 row_mask:0xf bank_mask:0xf
	v_fmac_f32_dpp v56, v56, v52 row_shr:8 row_mask:0xf bank_mask:0xf
	v_fmac_f32_dpp v57, v57, v53 row_shr:8 row_mask:0xf bank_mask:0xf
	v_fmac_f32_dpp v58, v58, v54 row_shr:8 row_mask:0xf bank_mask:0xf
	v_fmac_f32_dpp v59, v59, v55 row_shr:8 row_mask:0xf bank_mask:0xf
	v_mul_f32_dpp v52, v52, v52 row_shr:8 row_mask:0xf bank_mask:0xf
	v_mul_f32_dpp v53, v53, v53 row_shr:8 row_mask:0xf bank_mask:0xf
	v_mul_f32_dpp v54, v54, v54 row_shr:8 row_mask:0xf bank_mask:0xf
	v_mul_f32_dpp v55, v55, v55 row_shr:8 row_mask:0xf bank_mask:0xf
	v_fmac_f32_dpp v56, v56, v52 row_bcast:15 row_mask:0xa bank_mask:0xf
	v_fmac_f32_dpp v57, v57, v53 row_bcast:15 row_mask:0xa bank_mask:0xf
	v_fmac_f32_dpp v58, v58, v54 row_bcast:15 row_mask:0xa bank_mask:0xf
	v_fmac_f32_dpp v59, v59, v55 row_bcast:15 row_mask:0xa bank_mask:0xf
	v_mul_f32_dpp v52, v52, v52 row_bcast:15 row_mask:0xa bank_mask:0xf
	v_mul_f32_dpp v53, v53, v53 row_bcast:15 row_mask:0xa bank_mask:0xf
	v_mul_f32_dpp v54, v54, v54 row_bcast:15 row_mask:0xa bank_mask:0xf
	v_mul_f32_dpp v55, v55, v55 row_bcast:15 row_mask:0xa bank_mask:0xf
	ds_read_b128 v[0:3], v234 offset:39168
	v_exp_f32_e32 v8, v8
	v_exp_f32_e32 v9, v9
	v_exp_f32_e32 v10, v10
	v_exp_f32_e32 v11, v11
	v_exp_f32_e32 v24, v24
	v_exp_f32_e32 v25, v25
	v_exp_f32_e32 v26, v26
	v_exp_f32_e32 v27, v27
	v_pk_add_f32 v[8:9], v[8:9], v[240:241] op_sel_hi:[1,0]
	v_pk_add_f32 v[10:11], v[10:11], v[240:241] op_sel_hi:[1,0]
	v_pk_add_f32 v[24:25], v[24:25], v[240:241] op_sel_hi:[1,0]
	v_pk_add_f32 v[26:27], v[26:27], v[240:241] op_sel_hi:[1,0]
	v_rcp_f32_e32 v8, v8
	v_rcp_f32_e32 v9, v9
	v_rcp_f32_e32 v10, v10
	v_rcp_f32_e32 v11, v11
	v_rcp_f32_e32 v24, v24
	v_rcp_f32_e32 v25, v25
	v_rcp_f32_e32 v26, v26
	v_rcp_f32_e32 v27, v27
	v_mul_f32_e32 v200, v61, v24
	v_mul_f32_e32 v201, v62, v25
	v_mul_f32_e32 v202, v66, v26
	v_mul_f32_e32 v203, v67, v27
	s_waitcnt lgkmcnt(0)
; #define LAS __attribute__((address_space(3)))
; __device__ __forceinline__ float ex2(float x) { return __builtin_amdgcn_exp2f(x); }
; __device__ __forceinline__ float rcpf_(float x) { return __builtin_amdgcn_rcpf(x); }
; __device__ __forceinline__ void lru_phase(const Ptrs& P, LAS unsigned char* lds, int G, int wave, int lane, int tid) {
;     ...
; #pragma unroll
;             for (int i4 = 0; i4 < 4; ++i4) { if (mt == 2 && i4 >= 2) continue;
;                 const int s = 2 * mt + (i4 >> 1), half = i4 & 1, ch0 = 16 * s + 8 * half + 4 * hh;
;                 const f32x4 ls2 = *(const LAS f32x4*)(par + 7 * LB + ch0);
;                 float A4[4], B4[4];
; #pragma unroll
;                 for (int q = 0; q < 4; ++q) { const int i = 4 * i4 + q;
;                     const float rg = rcpf_(1.0f + ex2(gr[i])), ig = rcpf_(1.0f + ex2(gi[i]));
;                     const float la2 = ls2[q] * rg, a = ex2(la2), xx = (2.0f * LN2) * la2;
;                     const float poly = -xx * (1.0f + xx * (0.5f + xx * ((1.0f / 6.0f) + xx * ((1.0f / 24.0f) + xx * (1.0f / 120.0f)))));
;                     const float om = (xx > -0.25f) ? poly : (1.0f - a * a);
;                     A4[q] = a; B4[q] = __builtin_amdgcn_sqrtf(om) * (ig * xc[s][half][q]); }
;                 asm volatile("s_nop 1\n\t"
;                     LRU_DPP4("row_shr:1 row_mask:0xf bank_mask:0xf") LRU_DPP4("row_shr:2 row_mask:0xf bank_mask:0xf") LRU_DPP4("row_shr:4 row_mask:0xf bank_mask:0xf")
;                     LRU_DPP4("row_shr:8 row_mask:0xf bank_mask:0xf") LRU_DPP4("row_bcast:15 row_mask:0xa bank_mask:0xf")
;                     : "+v"(A4[0]), "+v"(A4[1]), "+v"(A4[2]), "+v"(A4[3]), "+v"(B4[0]), "+v"(B4[1]), "+v"(B4[2]), "+v"(B4[3]));
; #pragma unroll
;                 for (int q = 0; q < 4; ++q) { Av[s][half][q] = A4[q]; xc[s][half][q] = B4[q]; }
;                 __builtin_amdgcn_sched_barrier(0); }
	v_pk_mul_f32 v[8:9], v[8:9], v[0:1]
	v_pk_mul_f32 v[10:11], v[10:11], v[2:3]
	v_pk_mul_f32 v[204:205], v[8:9], v[242:243] op_sel_hi:[1,0]
	v_pk_mul_f32 v[206:207], v[10:11], v[242:243] op_sel_hi:[1,0]
	v_exp_f32_e32 v60, v8
	v_exp_f32_e32 v61, v9
	v_exp_f32_e32 v62, v10
	v_exp_f32_e32 v63, v11
	v_pk_fma_f32 v[208:209], v[204:205], v[244:245], v[238:239] op_sel_hi:[1,0,0]
	v_pk_fma_f32 v[210:211], v[206:207], v[244:245], v[238:239] op_sel_hi:[1,0,0]
	v_pk_fma_f32 v[208:209], v[204:205], v[208:209], v[246:247] op_sel_hi:[1,1,0]
	v_pk_fma_f32 v[210:211], v[206:207], v[210:211], v[246:247] op_sel_hi:[1,1,0]
	v_pk_fma_f32 v[208:209], v[204:205], v[208:209], v[248:249] op_sel_hi:[1,1,0]
	v_pk_fma_f32 v[210:211], v[206:207], v[210:211], v[248:249] op_sel_hi:[1,1,0]
	v_pk_fma_f32 v[208:209], v[204:205], v[208:209], v[240:241] op_sel_hi:[1,1,0]
	v_pk_fma_f32 v[210:211], v[206:207], v[210:211], v[240:241] op_sel_hi:[1,1,0]
	v_pk_mul_f32 v[208:209], v[208:209], v[204:205] neg_lo:[0,1] neg_hi:[0,1]
	v_pk_mul_f32 v[210:211], v[210:211], v[206:207] neg_lo:[0,1] neg_hi:[0,1]
	v_pk_fma_f32 v[212:213], v[60:61], v[60:61], v[240:241] op_sel_hi:[1,1,0] neg_lo:[1,0,0] neg_hi:[1,0,0]
	v_pk_fma_f32 v[214:215], v[62:63], v[62:63], v[240:241] op_sel_hi:[1,1,0] neg_lo:[1,0,0] neg_hi:[1,0,0]
	v_cmp_lt_f32_e64 s[70:71], s29, v204
	v_cmp_lt_f32_e64 s[72:73], s29, v205
	v_cmp_lt_f32_e64 s[74:75], s29, v206
	v_cmp_lt_f32_e64 s[76:77], s29, v207
	v_cndmask_b32_e64 v212, v212, v208, s[70:71]
	v_cndmask_b32_e64 v213, v213, v209, s[72:73]
	v_cndmask_b32_e64 v214, v214, v210, s[74:75]
	v_cndmask_b32_e64 v215, v215, v211, s[76:77]
	v_sqrt_f32_e32 v212, v212
	v_sqrt_f32_e32 v213, v213
	v_sqrt_f32_e32 v214, v214
	v_sqrt_f32_e32 v215, v215
	v_pk_mul_f32 v[64:65], v[200:201], v[212:213]
	v_pk_mul_f32 v[66:67], v[202:203], v[214:215]
	s_nop 1
	v_fmac_f32_dpp v64, v64, v60 row_shr:1 row_mask:0xf bank_mask:0xf
	v_fmac_f32_dpp v65, v65, v61 row_shr:1 row_mask:0xf bank_mask:0xf
	v_fmac_f32_dpp v66, v66, v62 row_shr:1 row_mask:0xf bank_mask:0xf
	v_fmac_f32_dpp v67, v67, v63 row_shr:1 row_mask:0xf bank_mask:0xf
	v_mul_f32_dpp v60, v60, v60 row_shr:1 row_mask:0xf bank_mask:0xf
	v_mul_f32_dpp v61, v61, v61 row_shr:1 row_mask:0xf bank_mask:0xf
	v_mul_f32_dpp v62, v62, v62 row_shr:1 row_mask:0xf bank_mask:0xf
	v_mul_f32_dpp v63, v63, v63 row_shr:1 row_mask:0xf bank_mask:0xf
	v_fmac_f32_dpp v64, v64, v60 row_shr:2 row_mask:0xf bank_mask:0xf
	v_fmac_f32_dpp v65, v65, v61 row_shr:2 row_mask:0xf bank_mask:0xf
	v_fmac_f32_dpp v66, v66, v62 row_shr:2 row_mask:0xf bank_mask:0xf
	v_fmac_f32_dpp v67, v67, v63 row_shr:2 row_mask:0xf bank_mask:0xf
	v_mul_f32_dpp v60, v60, v60 row_shr:2 row_mask:0xf bank_mask:0xf
	v_mul_f32_dpp v61, v61, v61 row_shr:2 row_mask:0xf bank_mask:0xf
	v_mul_f32_dpp v62, v62, v62 row_shr:2 row_mask:0xf bank_mask:0xf
	v_mul_f32_dpp v63, v63, v63 row_shr:2 row_mask:0xf bank_mask:0xf
	v_fmac_f32_dpp v64, v64, v60 row_shr:4 row_mask:0xf bank_mask:0xf
	v_fmac_f32_dpp v65, v65, v61 row_shr:4 row_mask:0xf bank_mask:0xf
	v_fmac_f32_dpp v66, v66, v62 row_shr:4 row_mask:0xf bank_mask:0xf
	v_fmac_f32_dpp v67, v67, v63 row_shr:4 row_mask:0xf bank_mask:0xf
	v_mul_f32_dpp v60, v60, v60 row_shr:4 row_mask:0xf bank_mask:0xf
	v_mul_f32_dpp v61, v61, v61 row_shr:4 row_mask:0xf bank_mask:0xf
	v_mul_f32_dpp v62, v62, v62 row_shr:4 row_mask:0xf bank_mask:0xf
	v_mul_f32_dpp v63, v63, v63 row_shr:4 row_mask:0xf bank_mask:0xf
	v_fmac_f32_dpp v64, v64, v60 row_shr:8 row_mask:0xf bank_mask:0xf
	v_fmac_f32_dpp v65, v65, v61 row_shr:8 row_mask:0xf bank_mask:0xf
	v_fmac_f32_dpp v66, v66, v62 row_shr:8 row_mask:0xf bank_mask:0xf
	v_fmac_f32_dpp v67, v67, v63 row_shr:8 row_mask:0xf bank_mask:0xf
	v_mul_f32_dpp v60, v60, v60 row_shr:8 row_mask:0xf bank_mask:0xf
	v_mul_f32_dpp v61, v61, v61 row_shr:8 row_mask:0xf bank_mask:0xf
	v_mul_f32_dpp v62, v62, v62 row_shr:8 row_mask:0xf bank_mask:0xf
	v_mul_f32_dpp v63, v63, v63 row_shr:8 row_mask:0xf bank_mask:0xf
	v_fmac_f32_dpp v64, v64, v60 row_bcast:15 row_mask:0xa bank_mask:0xf
	v_fmac_f32_dpp v65, v65, v61 row_bcast:15 row_mask:0xa bank_mask:0xf
	v_fmac_f32_dpp v66, v66, v62 row_bcast:15 row_mask:0xa bank_mask:0xf
	v_fmac_f32_dpp v67, v67, v63 row_bcast:15 row_mask:0xa bank_mask:0xf
	v_mul_f32_dpp v60, v60, v60 row_bcast:15 row_mask:0xa bank_mask:0xf
	v_mul_f32_dpp v61, v61, v61 row_bcast:15 row_mask:0xa bank_mask:0xf
	v_mul_f32_dpp v62, v62, v62 row_bcast:15 row_mask:0xa bank_mask:0xf
	v_mul_f32_dpp v63, v63, v63 row_bcast:15 row_mask:0xa bank_mask:0xf
	ds_read_b128 v[0:3], v234 offset:39200
	v_exp_f32_e32 v12, v12
	v_exp_f32_e32 v13, v13
	v_exp_f32_e32 v14, v14
	v_exp_f32_e32 v15, v15
	v_exp_f32_e32 v28, v28
	v_exp_f32_e32 v29, v29
	v_exp_f32_e32 v30, v30
	v_exp_f32_e32 v31, v31
	v_pk_add_f32 v[12:13], v[12:13], v[240:241] op_sel_hi:[1,0]
	v_pk_add_f32 v[14:15], v[14:15], v[240:241] op_sel_hi:[1,0]
	v_pk_add_f32 v[28:29], v[28:29], v[240:241] op_sel_hi:[1,0]
	v_pk_add_f32 v[30:31], v[30:31], v[240:241] op_sel_hi:[1,0]
	v_rcp_f32_e32 v12, v12
	v_rcp_f32_e32 v13, v13
	v_rcp_f32_e32 v14, v14
	v_rcp_f32_e32 v15, v15
	v_rcp_f32_e32 v28, v28
	v_rcp_f32_e32 v29, v29
	v_rcp_f32_e32 v30, v30
	v_rcp_f32_e32 v31, v31
	v_mul_f32_e32 v200, v69, v28
	v_mul_f32_e32 v201, v70, v29
	v_mul_f32_e32 v202, v74, v30
	v_mul_f32_e32 v203, v75, v31
	s_waitcnt lgkmcnt(0)
; #define LAS __attribute__((address_space(3)))
; __device__ __forceinline__ float ex2(float x) { return __builtin_amdgcn_exp2f(x); }
; __device__ __forceinline__ float rcpf_(float x) { return __builtin_amdgcn_rcpf(x); }
; __device__ __forceinline__ void lru_phase(const Ptrs& P, LAS unsigned char* lds, int G, int wave, int lane, int tid) {
;     ...
; #pragma unroll
;             for (int i4 = 0; i4 < 4; ++i4) { if (mt == 2 && i4 >= 2) continue;
;                 const int s = 2 * mt + (i4 >> 1), half = i4 & 1, ch0 = 16 * s + 8 * half + 4 * hh;
;                 const f32x4 ls2 = *(const LAS f32x4*)(par + 7 * LB + ch0);
;                 float A4[4], B4[4];
; #pragma unroll
;                 for (int q = 0; q < 4; ++q) { const int i = 4 * i4 + q;
;                     const float rg = rcpf_(1.0f + ex2(gr[i])), ig = rcpf_(1.0f + ex2(gi[i]));
;                     const float la2 = ls2[q] * rg, a = ex2(la2), xx = (2.0f * LN2) * la2;
;                     const float poly = -xx * (1.0f + xx * (0.5f + xx * ((1.0f / 6.0f) + xx * ((1.0f / 24.0f) + xx * (1.0f / 120.0f)))));
;                     const float om = (xx > -0.25f) ? poly : (1.0f - a * a);
;                     A4[q] = a; B4[q] = __builtin_amdgcn_sqrtf(om) * (ig * xc[s][half][q]); }
;                 asm volatile("s_nop 1\n\t"
;                     LRU_DPP4("row_shr:1 row_mask:0xf bank_mask:0xf") LRU_DPP4("row_shr:2 row_mask:0xf bank_mask:0xf") LRU_DPP4("row_shr:4 row_mask:0xf bank_mask:0xf")
;                     LRU_DPP4("row_shr:8 row_mask:0xf bank_mask:0xf") LRU_DPP4("row_bcast:15 row_mask:0xa bank_mask:0xf")
;                     : "+v"(A4[0]), "+v"(A4[1]), "+v"(A4[2]), "+v"(A4[3]), "+v"(B4[0]), "+v"(B4[1]), "+v"(B4[2]), "+v"(B4[3]));
; #pragma unroll
;                 for (int q = 0; q < 4; ++q) { Av[s][half][q] = A4[q]; xc[s][half][q] = B4[q]; }
;                 __builtin_amdgcn_sched_barrier(0); }
	v_pk_mul_f32 v[12:13], v[12:13], v[0:1]
	v_pk_mul_f32 v[14:15], v[14:15], v[2:3]
	v_pk_mul_f32 v[204:205], v[12:13], v[242:243] op_sel_hi:[1,0]
	v_pk_mul_f32 v[206:207], v[14:15], v[242:243] op_sel_hi:[1,0]
	v_exp_f32_e32 v68, v12
	v_exp_f32_e32 v69, v13
	v_exp_f32_e32 v70, v14
	v_exp_f32_e32 v71, v15
	v_pk_fma_f32 v[208:209], v[204:205], v[244:245], v[238:239] op_sel_hi:[1,0,0]
	v_pk_fma_f32 v[210:211], v[206:207], v[244:245], v[238:239] op_sel_hi:[1,0,0]
	v_pk_fma_f32 v[208:209], v[204:205], v[208:209], v[246:247] op_sel_hi:[1,1,0]
	v_pk_fma_f32 v[210:211], v[206:207], v[210:211], v[246:247] op_sel_hi:[1,1,0]
	v_pk_fma_f32 v[208:209], v[204:205], v[208:209], v[248:249] op_sel_hi:[1,1,0]
	v_pk_fma_f32 v[210:211], v[206:207], v[210:211], v[248:249] op_sel_hi:[1,1,0]
	v_pk_fma_f32 v[208:209], v[204:205], v[208:209], v[240:241] op_sel_hi:[1,1,0]
	v_pk_fma_f32 v[210:211], v[206:207], v[210:211], v[240:241] op_sel_hi:[1,1,0]
	v_pk_mul_f32 v[208:209], v[208:209], v[204:205] neg_lo:[0,1] neg_hi:[0,1]
	v_pk_mul_f32 v[210:211], v[210:211], v[206:207] neg_lo:[0,1] neg_hi:[0,1]
	v_pk_fma_f32 v[212:213], v[68:69], v[68:69], v[240:241] op_sel_hi:[1,1,0] neg_lo:[1,0,0] neg_hi:[1,0,0]
	v_pk_fma_f32 v[214:215], v[70:71], v[70:71], v[240:241] op_sel_hi:[1,1,0] neg_lo:[1,0,0] neg_hi:[1,0,0]
	v_cmp_lt_f32_e64 s[70:71], s29, v204
	v_cmp_lt_f32_e64 s[72:73], s29, v205
	v_cmp_lt_f32_e64 s[74:75], s29, v206
	v_cmp_lt_f32_e64 s[76:77], s29, v207
	v_cndmask_b32_e64 v212, v212, v208, s[70:71]
	v_cndmask_b32_e64 v213, v213, v209, s[72:73]
	v_cndmask_b32_e64 v214, v214, v210, s[74:75]
	v_cndmask_b32_e64 v215, v215, v211, s[76:77]
	v_sqrt_f32_e32 v212, v212
	v_sqrt_f32_e32 v213, v213
	v_sqrt_f32_e32 v214, v214
	v_sqrt_f32_e32 v215, v215
	v_pk_mul_f32 v[72:73], v[200:201], v[212:213]
	v_pk_mul_f32 v[74:75], v[202:203], v[214:215]
	s_nop 1
	v_fmac_f32_dpp v72, v72, v68 row_shr:1 row_mask:0xf bank_mask:0xf
	v_fmac_f32_dpp v73, v73, v69 row_shr:1 row_mask:0xf bank_mask:0xf
	v_fmac_f32_dpp v74, v74, v70 row_shr:1 row_mask:0xf bank_mask:0xf
	v_fmac_f32_dpp v75, v75, v71 row_shr:1 row_mask:0xf bank_mask:0xf
	v_mul_f32_dpp v68, v68, v68 row_shr:1 row_mask:0xf bank_mask:0xf
	v_mul_f32_dpp v69, v69, v69 row_shr:1 row_mask:0xf bank_mask:0xf
	v_mul_f32_dpp v70, v70, v70 row_shr:1 row_mask:0xf bank_mask:0xf
	v_mul_f32_dpp v71, v71, v71 row_shr:1 row_mask:0xf bank_mask:0xf
	v_fmac_f32_dpp v72, v72, v68 row_shr:2 row_mask:0xf bank_mask:0xf
	v_fmac_f32_dpp v73, v73, v69 row_shr:2 row_mask:0xf bank_mask:0xf
	v_fmac_f32_dpp v74, v74, v70 row_shr:2 row_mask:0xf bank_mask:0xf
	v_fmac_f32_dpp v75, v75, v71 row_shr:2 row_mask:0xf bank_mask:0xf
	v_mul_f32_dpp v68, v68, v68 row_shr:2 row_mask:0xf bank_mask:0xf
	v_mul_f32_dpp v69, v69, v69 row_shr:2 row_mask:0xf bank_mask:0xf
	v_mul_f32_dpp v70, v70, v70 row_shr:2 row_mask:0xf bank_mask:0xf
	v_mul_f32_dpp v71, v71, v71 row_shr:2 row_mask:0xf bank_mask:0xf
	v_fmac_f32_dpp v72, v72, v68 row_shr:4 row_mask:0xf bank_mask:0xf
	v_fmac_f32_dpp v73, v73, v69 row_shr:4 row_mask:0xf bank_mask:0xf
	v_fmac_f32_dpp v74, v74, v70 row_shr:4 row_mask:0xf bank_mask:0xf
	v_fmac_f32_dpp v75, v75, v71 row_shr:4 row_mask:0xf bank_mask:0xf
	v_mul_f32_dpp v68, v68, v68 row_shr:4 row_mask:0xf bank_mask:0xf
	v_mul_f32_dpp v69, v69, v69 row_shr:4 row_mask:0xf bank_mask:0xf
	v_mul_f32_dpp v70, v70, v70 row_shr:4 row_mask:0xf bank_mask:0xf
	v_mul_f32_dpp v71, v71, v71 row_shr:4 row_mask:0xf bank_mask:0xf
	v_fmac_f32_dpp v72, v72, v68 row_shr:8 row_mask:0xf bank_mask:0xf
	v_fmac_f32_dpp v73, v73, v69 row_shr:8 row_mask:0xf bank_mask:0xf
	v_fmac_f32_dpp v74, v74, v70 row_shr:8 row_mask:0xf bank_mask:0xf
	v_fmac_f32_dpp v75, v75, v71 row_shr:8 row_mask:0xf bank_mask:0xf
	v_mul_f32_dpp v68, v68, v68 row_shr:8 row_mask:0xf bank_mask:0xf
	v_mul_f32_dpp v69, v69, v69 row_shr:8 row_mask:0xf bank_mask:0xf
	v_mul_f32_dpp v70, v70, v70 row_shr:8 row_mask:0xf bank_mask:0xf
	v_mul_f32_dpp v71, v71, v71 row_shr:8 row_mask:0xf bank_mask:0xf
	v_fmac_f32_dpp v72, v72, v68 row_bcast:15 row_mask:0xa bank_mask:0xf
	v_fmac_f32_dpp v73, v73, v69 row_bcast:15 row_mask:0xa bank_mask:0xf
	v_fmac_f32_dpp v74, v74, v70 row_bcast:15 row_mask:0xa bank_mask:0xf
	v_fmac_f32_dpp v75, v75, v71 row_bcast:15 row_mask:0xa bank_mask:0xf
	v_mul_f32_dpp v68, v68, v68 row_bcast:15 row_mask:0xa bank_mask:0xf
	v_mul_f32_dpp v69, v69, v69 row_bcast:15 row_mask:0xa bank_mask:0xf
	v_mul_f32_dpp v70, v70, v70 row_bcast:15 row_mask:0xa bank_mask:0xf
	v_mul_f32_dpp v71, v71, v71 row_bcast:15 row_mask:0xa bank_mask:0xf

; #define LAS __attribute__((address_space(3)))
; __device__ __forceinline__ void lru_phase(const Ptrs& P, LAS unsigned char* lds, int G, int wave, int lane, int tid) {
;     ...
;         for (int mt = 0; mt < 3; ++mt) {
;             f32x16 gr, gi;
; #pragma unroll
;             for (int i = 0; i < 16; ++i) { gr[i] = 0.f; gi[i] = 0.f; }
;             const LAS bf16x8* wa = (const LAS bf16x8*)(lds + L_WGF) + (size_t)(mt * 6) * 64 + lane;
;             const LAS bf16x8* wb = (const LAS bf16x8*)(lds + L_WGF) + (size_t)((3 + mt) * 6) * 64 + lane;
; #pragma unroll
;             for (int s = 0; s < 5; ++s) { gr = MFMA32(wa[s * 64], xf[s], gr); gi = MFMA32(wb[s * 64], xf[s], gi); }
;             gr = MFMA32(wa[5 * 64], xone, gr); gi = MFMA32(wb[5 * 64], xone, gi);
;             __builtin_amdgcn_sched_barrier(0);
; #pragma unroll
;             for (int i4 = 0; i4 < 4; ++i4) { if (mt == 2 && i4 >= 2) continue;
;                 const int s = 2 * mt + (i4 >> 1), half = i4 & 1, ch0 = 16 * s + 8 * half + 4 * hh;
;                 const f32x4 ls2 = *(const LAS f32x4*)(par + 7 * LB + ch0);
;                 float A4[4], B4[4];
; #pragma unroll
;                 for (int q = 0; q < 4; ++q) { const int i = 4 * i4 + q;
;                     const float rg = rcpf_(1.0f + ex2(gr[i])), ig = rcpf_(1.0f + ex2(gi[i]));
;                     const float la2 = ls2[q] * rg, a = ex2(la2), xx = (2.0f * LN2) * la2;
;                     const float poly = -xx * (1.0f + xx * (0.5f + xx * ((1.0f / 6.0f) + xx * ((1.0f / 24.0f) + xx * (1.0f / 120.0f)))));
;                     const float om = (xx > -0.25f) ? poly : (1.0f - a * a);
;                     A4[q] = a; B4[q] = __builtin_amdgcn_sqrtf(om) * (ig * xc[s][half][q]); }
;                 asm volatile("s_nop 1\n\t"
;                     LRU_DPP4("row_shr:1 row_mask:0xf bank_mask:0xf") LRU_DPP4("row_shr:2 row_mask:0xf bank_mask:0xf") LRU_DPP4("row_shr:4 row_mask:0xf bank_mask:0xf")
;                     LRU_DPP4("row_shr:8 row_mask:0xf bank_mask:0xf") LRU_DPP4("row_bcast:15 row_mask:0xa bank_mask:0xf")
;                     : "+v"(A4[0]), "+v"(A4[1]), "+v"(A4[2]), "+v"(A4[3]), "+v"(B4[0]), "+v"(B4[1]), "+v"(B4[2]), "+v"(B4[3]));
; #pragma unroll
;                 for (int q = 0; q < 4; ++q) { Av[s][half][q] = A4[q]; xc[s][half][q] = B4[q]; }
;                 __builtin_amdgcn_sched_barrier(0); }
	ds_read_b128 v[0:3], v237 offset:6144
	ds_read_b128 v[140:143], v237 offset:7168
	ds_read_b128 v[16:19], v237 offset:24576
	ds_read_b128 v[144:147], v237 offset:25600
	s_waitcnt lgkmcnt(3)
	v_mfma_f32_32x32x16_bf16 v[0:15], v[0:3], v[36:39], 0
	s_waitcnt lgkmcnt(1)
	v_mfma_f32_32x32x16_bf16 v[16:31], v[16:19], v[36:39], 0
	v_mfma_f32_32x32x16_bf16 v[0:15], v[140:143], v[40:43], v[0:15]
	s_waitcnt lgkmcnt(0)
	v_mfma_f32_32x32x16_bf16 v[16:31], v[144:147], v[40:43], v[16:31]
	ds_read_b128 v[140:143], v237 offset:8192
	ds_read_b128 v[144:147], v237 offset:9216
	s_waitcnt lgkmcnt(1)
	v_mfma_f32_32x32x16_bf16 v[0:15], v[140:143], v[76:79], v[0:15]
	ds_read_b128 v[140:143], v237 offset:26624
	ds_read_b128 v[148:151], v237 offset:27648
	s_waitcnt lgkmcnt(1)
	v_mfma_f32_32x32x16_bf16 v[16:31], v[140:143], v[76:79], v[16:31]
	v_mfma_f32_32x32x16_bf16 v[0:15], v[144:147], v[112:115], v[0:15]
	ds_read_b128 v[140:143], v237 offset:10240
	ds_read_b128 v[144:147], v237 offset:11264
	s_waitcnt lgkmcnt(2)
	v_mfma_f32_32x32x16_bf16 v[16:31], v[148:151], v[112:115], v[16:31]
	s_waitcnt lgkmcnt(1)
	v_mfma_f32_32x32x16_bf16 v[0:15], v[140:143], v[124:127], v[0:15]
	ds_read_b128 v[140:143], v237 offset:28672
	ds_read_b128 v[148:151], v237 offset:29696
	s_waitcnt lgkmcnt(1)
	v_mfma_f32_32x32x16_bf16 v[16:31], v[140:143], v[124:127], v[16:31]
	v_mfma_f32_32x32x16_bf16 v[0:15], v[144:147], v[32:35], v[0:15]
	s_waitcnt lgkmcnt(0)
	v_mfma_f32_32x32x16_bf16 v[16:31], v[148:151], v[32:35], v[16:31]
	s_nop 9
	ds_read_b128 v[140:143], v234 offset:39232
	v_exp_f32_e32 v0, v0
	v_exp_f32_e32 v1, v1
	v_exp_f32_e32 v2, v2
	v_exp_f32_e32 v3, v3
	v_exp_f32_e32 v16, v16
	v_exp_f32_e32 v17, v17
	v_exp_f32_e32 v18, v18
	v_exp_f32_e32 v19, v19
	v_pk_add_f32 v[0:1], v[0:1], v[240:241] op_sel_hi:[1,0]
	v_pk_add_f32 v[2:3], v[2:3], v[240:241] op_sel_hi:[1,0]
	v_pk_add_f32 v[16:17], v[16:17], v[240:241] op_sel_hi:[1,0]
	v_pk_add_f32 v[18:19], v[18:19], v[240:241] op_sel_hi:[1,0]
	v_rcp_f32_e32 v0, v0
	v_rcp_f32_e32 v1, v1
	v_rcp_f32_e32 v2, v2
	v_rcp_f32_e32 v3, v3
	v_rcp_f32_e32 v16, v16
	v_rcp_f32_e32 v17, v17
	v_rcp_f32_e32 v18, v18
	v_rcp_f32_e32 v19, v19
	v_mul_f32_e32 v200, v81, v16
	v_mul_f32_e32 v201, v82, v17
	v_mul_f32_e32 v202, v86, v18
	v_mul_f32_e32 v203, v87, v19
	s_waitcnt lgkmcnt(0)
	v_pk_mul_f32 v[0:1], v[0:1], v[140:141]
	v_pk_mul_f32 v[2:3], v[2:3], v[142:143]
	v_pk_mul_f32 v[204:205], v[0:1], v[242:243] op_sel_hi:[1,0]
	v_pk_mul_f32 v[206:207], v[2:3], v[242:243] op_sel_hi:[1,0]
	v_exp_f32_e32 v80, v0
	v_exp_f32_e32 v81, v1
	v_exp_f32_e32 v82, v2
	v_exp_f32_e32 v83, v3
	v_pk_fma_f32 v[208:209], v[204:205], v[244:245], v[238:239] op_sel_hi:[1,0,0]
	v_pk_fma_f32 v[210:211], v[206:207], v[244:245], v[238:239] op_sel_hi:[1,0,0]
	v_pk_fma_f32 v[208:209], v[204:205], v[208:209], v[246:247] op_sel_hi:[1,1,0]
	v_pk_fma_f32 v[210:211], v[206:207], v[210:211], v[246:247] op_sel_hi:[1,1,0]
	v_pk_fma_f32 v[208:209], v[204:205], v[208:209], v[248:249] op_sel_hi:[1,1,0]
	v_pk_fma_f32 v[210:211], v[206:207], v[210:211], v[248:249] op_sel_hi:[1,1,0]
	v_pk_fma_f32 v[208:209], v[204:205], v[208:209], v[240:241] op_sel_hi:[1,1,0]
	v_pk_fma_f32 v[210:211], v[206:207], v[210:211], v[240:241] op_sel_hi:[1,1,0]
	v_pk_mul_f32 v[208:209], v[208:209], v[204:205] neg_lo:[0,1] neg_hi:[0,1]
	v_pk_mul_f32 v[210:211], v[210:211], v[206:207] neg_lo:[0,1] neg_hi:[0,1]
	v_pk_fma_f32 v[212:213], v[80:81], v[80:81], v[240:241] op_sel_hi:[1,1,0] neg_lo:[1,0,0] neg_hi:[1,0,0]
	v_pk_fma_f32 v[214:215], v[82:83], v[82:83], v[240:241] op_sel_hi:[1,1,0] neg_lo:[1,0,0] neg_hi:[1,0,0]
	v_cmp_lt_f32_e64 s[70:71], s29, v204
	v_cmp_lt_f32_e64 s[72:73], s29, v205
	v_cmp_lt_f32_e64 s[74:75], s29, v206
	v_cmp_lt_f32_e64 s[76:77], s29, v207
	v_cndmask_b32_e64 v212, v212, v208, s[70:71]
	v_cndmask_b32_e64 v213, v213, v209, s[72:73]
	v_cndmask_b32_e64 v214, v214, v210, s[74:75]
	v_cndmask_b32_e64 v215, v215, v211, s[76:77]
	v_sqrt_f32_e32 v212, v212
	v_sqrt_f32_e32 v213, v213
	v_sqrt_f32_e32 v214, v214
	v_sqrt_f32_e32 v215, v215
	v_pk_mul_f32 v[84:85], v[200:201], v[212:213]
	v_pk_mul_f32 v[86:87], v[202:203], v[214:215]
	s_nop 1
	v_fmac_f32_dpp v84, v84, v80 row_shr:1 row_mask:0xf bank_mask:0xf
	v_fmac_f32_dpp v85, v85, v81 row_shr:1 row_mask:0xf bank_mask:0xf
	v_fmac_f32_dpp v86, v86, v82 row_shr:1 row_mask:0xf bank_mask:0xf
	v_fmac_f32_dpp v87, v87, v83 row_shr:1 row_mask:0xf bank_mask:0xf
	v_mul_f32_dpp v80, v80, v80 row_shr:1 row_mask:0xf bank_mask:0xf
	v_mul_f32_dpp v81, v81, v81 row_shr:1 row_mask:0xf bank_mask:0xf
	v_mul_f32_dpp v82, v82, v82 row_shr:1 row_mask:0xf bank_mask:0xf
	v_mul_f32_dpp v83, v83, v83 row_shr:1 row_mask:0xf bank_mask:0xf
	v_fmac_f32_dpp v84, v84, v80 row_shr:2 row_mask:0xf bank_mask:0xf
	v_fmac_f32_dpp v85, v85, v81 row_shr:2 row_mask:0xf bank_mask:0xf
	v_fmac_f32_dpp v86, v86, v82 row_shr:2 row_mask:0xf bank_mask:0xf
	v_fmac_f32_dpp v87, v87, v83 row_shr:2 row_mask:0xf bank_mask:0xf
	v_mul_f32_dpp v80, v80, v80 row_shr:2 row_mask:0xf bank_mask:0xf
	v_mul_f32_dpp v81, v81, v81 row_shr:2 row_mask:0xf bank_mask:0xf
	v_mul_f32_dpp v82, v82, v82 row_shr:2 row_mask:0xf bank_mask:0xf
	v_mul_f32_dpp v83, v83, v83 row_shr:2 row_mask:0xf bank_mask:0xf
	v_fmac_f32_dpp v84, v84, v80 row_shr:4 row_mask:0xf bank_mask:0xf
	v_fmac_f32_dpp v85, v85, v81 row_shr:4 row_mask:0xf bank_mask:0xf
	v_fmac_f32_dpp v86, v86, v82 row_shr:4 row_mask:0xf bank_mask:0xf
	v_fmac_f32_dpp v87, v87, v83 row_shr:4 row_mask:0xf bank_mask:0xf
	v_mul_f32_dpp v80, v80, v80 row_shr:4 row_mask:0xf bank_mask:0xf
	v_mul_f32_dpp v81, v81, v81 row_shr:4 row_mask:0xf bank_mask:0xf
	v_mul_f32_dpp v82, v82, v82 row_shr:4 row_mask:0xf bank_mask:0xf
; #define LAS __attribute__((address_space(3)))
; __device__ __forceinline__ float ex2(float x) { return __builtin_amdgcn_exp2f(x); }
; __device__ __forceinline__ float rcpf_(float x) { return __builtin_amdgcn_rcpf(x); }
; __device__ __forceinline__ void lru_phase(const Ptrs& P, LAS unsigned char* lds, int G, int wave, int lane, int tid) {
;     ...
; #pragma unroll
;             for (int i4 = 0; i4 < 4; ++i4) { if (mt == 2 && i4 >= 2) continue;
;                 const int s = 2 * mt + (i4 >> 1), half = i4 & 1, ch0 = 16 * s + 8 * half + 4 * hh;
;                 const f32x4 ls2 = *(const LAS f32x4*)(par + 7 * LB + ch0);
;                 float A4[4], B4[4];
; #pragma unroll
;                 for (int q = 0; q < 4; ++q) { const int i = 4 * i4 + q;
;                     const float rg = rcpf_(1.0f + ex2(gr[i])), ig = rcpf_(1.0f + ex2(gi[i]));
;                     const float la2 = ls2[q] * rg, a = ex2(la2), xx = (2.0f * LN2) * la2;
;                     const float poly = -xx * (1.0f + xx * (0.5f + xx * ((1.0f / 6.0f) + xx * ((1.0f / 24.0f) + xx * (1.0f / 120.0f)))));
;                     const float om = (xx > -0.25f) ? poly : (1.0f - a * a);
;                     A4[q] = a; B4[q] = __builtin_amdgcn_sqrtf(om) * (ig * xc[s][half][q]); }
;                 asm volatile("s_nop 1\n\t"
;                     LRU_DPP4("row_shr:1 row_mask:0xf bank_mask:0xf") LRU_DPP4("row_shr:2 row_mask:0xf bank_mask:0xf") LRU_DPP4("row_shr:4 row_mask:0xf bank_mask:0xf")
;                     LRU_DPP4("row_shr:8 row_mask:0xf bank_mask:0xf") LRU_DPP4("row_bcast:15 row_mask:0xa bank_mask:0xf")
;                     : "+v"(A4[0]), "+v"(A4[1]), "+v"(A4[2]), "+v"(A4[3]), "+v"(B4[0]), "+v"(B4[1]), "+v"(B4[2]), "+v"(B4[3]));
; #pragma unroll
;                 for (int q = 0; q < 4; ++q) { Av[s][half][q] = A4[q]; xc[s][half][q] = B4[q]; }
;                 __builtin_amdgcn_sched_barrier(0); }
	v_mul_f32_dpp v83, v83, v83 row_shr:4 row_mask:0xf bank_mask:0xf
	v_fmac_f32_dpp v84, v84, v80 row_shr:8 row_mask:0xf bank_mask:0xf
	v_fmac_f32_dpp v85, v85, v81 row_shr:8 row_mask:0xf bank_mask:0xf
	v_fmac_f32_dpp v86, v86, v82 row_shr:8 row_mask:0xf bank_mask:0xf
	v_fmac_f32_dpp v87, v87, v83 row_shr:8 row_mask:0xf bank_mask:0xf
	v_mul_f32_dpp v80, v80, v80 row_shr:8 row_mask:0xf bank_mask:0xf
	v_mul_f32_dpp v81, v81, v81 row_shr:8 row_mask:0xf bank_mask:0xf
	v_mul_f32_dpp v82, v82, v82 row_shr:8 row_mask:0xf bank_mask:0xf
	v_mul_f32_dpp v83, v83, v83 row_shr:8 row_mask:0xf bank_mask:0xf
	v_fmac_f32_dpp v84, v84, v80 row_bcast:15 row_mask:0xa bank_mask:0xf
	v_fmac_f32_dpp v85, v85, v81 row_bcast:15 row_mask:0xa bank_mask:0xf
	v_fmac_f32_dpp v86, v86, v82 row_bcast:15 row_mask:0xa bank_mask:0xf
	v_fmac_f32_dpp v87, v87, v83 row_bcast:15 row_mask:0xa bank_mask:0xf
	v_mul_f32_dpp v80, v80, v80 row_bcast:15 row_mask:0xa bank_mask:0xf
	v_mul_f32_dpp v81, v81, v81 row_bcast:15 row_mask:0xa bank_mask:0xf
	v_mul_f32_dpp v82, v82, v82 row_bcast:15 row_mask:0xa bank_mask:0xf
	v_mul_f32_dpp v83, v83, v83 row_bcast:15 row_mask:0xa bank_mask:0xf
	ds_read_b128 v[0:3], v234 offset:39264
	v_exp_f32_e32 v4, v4
	v_exp_f32_e32 v5, v5
	v_exp_f32_e32 v6, v6
	v_exp_f32_e32 v7, v7
	v_exp_f32_e32 v20, v20
	v_exp_f32_e32 v21, v21
	v_exp_f32_e32 v22, v22
	v_exp_f32_e32 v23, v23
	v_pk_add_f32 v[4:5], v[4:5], v[240:241] op_sel_hi:[1,0]
	v_pk_add_f32 v[6:7], v[6:7], v[240:241] op_sel_hi:[1,0]
	v_pk_add_f32 v[20:21], v[20:21], v[240:241] op_sel_hi:[1,0]
	v_pk_add_f32 v[22:23], v[22:23], v[240:241] op_sel_hi:[1,0]
	v_rcp_f32_e32 v4, v4
	v_rcp_f32_e32 v5, v5
	v_rcp_f32_e32 v6, v6
	v_rcp_f32_e32 v7, v7
	v_rcp_f32_e32 v20, v20
	v_rcp_f32_e32 v21, v21
	v_rcp_f32_e32 v22, v22
	v_rcp_f32_e32 v23, v23
	v_mul_f32_e32 v200, v89, v20
	v_mul_f32_e32 v201, v90, v21
	v_mul_f32_e32 v202, v94, v22
	v_mul_f32_e32 v203, v95, v23
	s_waitcnt lgkmcnt(0)
	v_pk_mul_f32 v[4:5], v[4:5], v[0:1]
	v_pk_mul_f32 v[6:7], v[6:7], v[2:3]
	v_pk_mul_f32 v[204:205], v[4:5], v[242:243] op_sel_hi:[1,0]
	v_pk_mul_f32 v[206:207], v[6:7], v[242:243] op_sel_hi:[1,0]
	v_exp_f32_e32 v88, v4
	v_exp_f32_e32 v89, v5
	v_exp_f32_e32 v90, v6
	v_exp_f32_e32 v91, v7
	v_pk_fma_f32 v[208:209], v[204:205], v[244:245], v[238:239] op_sel_hi:[1,0,0]
	v_pk_fma_f32 v[210:211], v[206:207], v[244:245], v[238:239] op_sel_hi:[1,0,0]
	v_pk_fma_f32 v[208:209], v[204:205], v[208:209], v[246:247] op_sel_hi:[1,1,0]
	v_pk_fma_f32 v[210:211], v[206:207], v[210:211], v[246:247] op_sel_hi:[1,1,0]
	v_pk_fma_f32 v[208:209], v[204:205], v[208:209], v[248:249] op_sel_hi:[1,1,0]
	v_pk_fma_f32 v[210:211], v[206:207], v[210:211], v[248:249] op_sel_hi:[1,1,0]
	v_pk_fma_f32 v[208:209], v[204:205], v[208:209], v[240:241] op_sel_hi:[1,1,0]
	v_pk_fma_f32 v[210:211], v[206:207], v[210:211], v[240:241] op_sel_hi:[1,1,0]
	v_pk_mul_f32 v[208:209], v[208:209], v[204:205] neg_lo:[0,1] neg_hi:[0,1]
	v_pk_mul_f32 v[210:211], v[210:211], v[206:207] neg_lo:[0,1] neg_hi:[0,1]
	v_pk_fma_f32 v[212:213], v[88:89], v[88:89], v[240:241] op_sel_hi:[1,1,0] neg_lo:[1,0,0] neg_hi:[1,0,0]
	v_pk_fma_f32 v[214:215], v[90:91], v[90:91], v[240:241] op_sel_hi:[1,1,0] neg_lo:[1,0,0] neg_hi:[1,0,0]
	v_cmp_lt_f32_e64 s[70:71], s29, v204
	v_cmp_lt_f32_e64 s[72:73], s29, v205
	v_cmp_lt_f32_e64 s[74:75], s29, v206
	v_cmp_lt_f32_e64 s[76:77], s29, v207
	v_cndmask_b32_e64 v212, v212, v208, s[70:71]
	v_cndmask_b32_e64 v213, v213, v209, s[72:73]
	v_cndmask_b32_e64 v214, v214, v210, s[74:75]
	v_cndmask_b32_e64 v215, v215, v211, s[76:77]
	v_sqrt_f32_e32 v212, v212
	v_sqrt_f32_e32 v213, v213
	v_sqrt_f32_e32 v214, v214
	v_sqrt_f32_e32 v215, v215
	v_pk_mul_f32 v[92:93], v[200:201], v[212:213]
	v_pk_mul_f32 v[94:95], v[202:203], v[214:215]
	s_nop 1
	v_fmac_f32_dpp v92, v92, v88 row_shr:1 row_mask:0xf bank_mask:0xf
	v_fmac_f32_dpp v93, v93, v89 row_shr:1 row_mask:0xf bank_mask:0xf
	v_fmac_f32_dpp v94, v94, v90 row_shr:1 row_mask:0xf bank_mask:0xf
	v_fmac_f32_dpp v95, v95, v91 row_shr:1 row_mask:0xf bank_mask:0xf
	v_mul_f32_dpp v88, v88, v88 row_shr:1 row_mask:0xf bank_mask:0xf
	v_mul_f32_dpp v89, v89, v89 row_shr:1 row_mask:0xf bank_mask:0xf
	v_mul_f32_dpp v90, v90, v90 row_shr:1 row_mask:0xf bank_mask:0xf
	v_mul_f32_dpp v91, v91, v91 row_shr:1 row_mask:0xf bank_mask:0xf
	v_fmac_f32_dpp v92, v92, v88 row_shr:2 row_mask:0xf bank_mask:0xf
	v_fmac_f32_dpp v93, v93, v89 row_shr:2 row_mask:0xf bank_mask:0xf
	v_fmac_f32_dpp v94, v94, v90 row_shr:2 row_mask:0xf bank_mask:0xf
	v_fmac_f32_dpp v95, v95, v91 row_shr:2 row_mask:0xf bank_mask:0xf
	v_mul_f32_dpp v88, v88, v88 row_shr:2 row_mask:0xf bank_mask:0xf
	v_mul_f32_dpp v89, v89, v89 row_shr:2 row_mask:0xf bank_mask:0xf
	v_mul_f32_dpp v90, v90, v90 row_shr:2 row_mask:0xf bank_mask:0xf
	v_mul_f32_dpp v91, v91, v91 row_shr:2 row_mask:0xf bank_mask:0xf
	v_fmac_f32_dpp v92, v92, v88 row_shr:4 row_mask:0xf bank_mask:0xf
	v_fmac_f32_dpp v93, v93, v89 row_shr:4 row_mask:0xf bank_mask:0xf
	v_fmac_f32_dpp v94, v94, v90 row_shr:4 row_mask:0xf bank_mask:0xf
	v_fmac_f32_dpp v95, v95, v91 row_shr:4 row_mask:0xf bank_mask:0xf
	v_mul_f32_dpp v88, v88, v88 row_shr:4 row_mask:0xf bank_mask:0xf
	v_mul_f32_dpp v89, v89, v89 row_shr:4 row_mask:0xf bank_mask:0xf
	v_mul_f32_dpp v90, v90, v90 row_shr:4 row_mask:0xf bank_mask:0xf
	v_mul_f32_dpp v91, v91, v91 row_shr:4 row_mask:0xf bank_mask:0xf
	v_fmac_f32_dpp v92, v92, v88 row_shr:8 row_mask:0xf bank_mask:0xf
	v_fmac_f32_dpp v93, v93, v89 row_shr:8 row_mask:0xf bank_mask:0xf
	v_fmac_f32_dpp v94, v94, v90 row_shr:8 row_mask:0xf bank_mask:0xf
	v_fmac_f32_dpp v95, v95, v91 row_shr:8 row_mask:0xf bank_mask:0xf
; #define LAS __attribute__((address_space(3)))
; __device__ __forceinline__ float ex2(float x) { return __builtin_amdgcn_exp2f(x); }
; __device__ __forceinline__ float rcpf_(float x) { return __builtin_amdgcn_rcpf(x); }
; __device__ __forceinline__ void lru_phase(const Ptrs& P, LAS unsigned char* lds, int G, int wave, int lane, int tid) {
;     ...
; #pragma unroll
;             for (int i4 = 0; i4 < 4; ++i4) { if (mt == 2 && i4 >= 2) continue;
;                 const int s = 2 * mt + (i4 >> 1), half = i4 & 1, ch0 = 16 * s + 8 * half + 4 * hh;
;                 const f32x4 ls2 = *(const LAS f32x4*)(par + 7 * LB + ch0);
;                 float A4[4], B4[4];
; #pragma unroll
;                 for (int q = 0; q < 4; ++q) { const int i = 4 * i4 + q;
;                     const float rg = rcpf_(1.0f + ex2(gr[i])), ig = rcpf_(1.0f + ex2(gi[i]));
;                     const float la2 = ls2[q] * rg, a = ex2(la2), xx = (2.0f * LN2) * la2;
;                     const float poly = -xx * (1.0f + xx * (0.5f + xx * ((1.0f / 6.0f) + xx * ((1.0f / 24.0f) + xx * (1.0f / 120.0f)))));
;                     const float om = (xx > -0.25f) ? poly : (1.0f - a * a);
;                     A4[q] = a; B4[q] = __builtin_amdgcn_sqrtf(om) * (ig * xc[s][half][q]); }
;                 asm volatile("s_nop 1\n\t"
;                     LRU_DPP4("row_shr:1 row_mask:0xf bank_mask:0xf") LRU_DPP4("row_shr:2 row_mask:0xf bank_mask:0xf") LRU_DPP4("row_shr:4 row_mask:0xf bank_mask:0xf")
;                     LRU_DPP4("row_shr:8 row_mask:0xf bank_mask:0xf") LRU_DPP4("row_bcast:15 row_mask:0xa bank_mask:0xf")
;                     : "+v"(A4[0]), "+v"(A4[1]), "+v"(A4[2]), "+v"(A4[3]), "+v"(B4[0]), "+v"(B4[1]), "+v"(B4[2]), "+v"(B4[3]));
; #pragma unroll
;                 for (int q = 0; q < 4; ++q) { Av[s][half][q] = A4[q]; xc[s][half][q] = B4[q]; }
;                 __builtin_amdgcn_sched_barrier(0); }
	v_mul_f32_dpp v88, v88, v88 row_shr:8 row_mask:0xf bank_mask:0xf
	v_mul_f32_dpp v89, v89, v89 row_shr:8 row_mask:0xf bank_mask:0xf
	v_mul_f32_dpp v90, v90, v90 row_shr:8 row_mask:0xf bank_mask:0xf
	v_mul_f32_dpp v91, v91, v91 row_shr:8 row_mask:0xf bank_mask:0xf
	v_fmac_f32_dpp v92, v92, v88 row_bcast:15 row_mask:0xa bank_mask:0xf
	v_fmac_f32_dpp v93, v93, v89 row_bcast:15 row_mask:0xa bank_mask:0xf
	v_fmac_f32_dpp v94, v94, v90 row_bcast:15 row_mask:0xa bank_mask:0xf
	v_fmac_f32_dpp v95, v95, v91 row_bcast:15 row_mask:0xa bank_mask:0xf
	v_mul_f32_dpp v88, v88, v88 row_bcast:15 row_mask:0xa bank_mask:0xf
	v_mul_f32_dpp v89, v89, v89 row_bcast:15 row_mask:0xa bank_mask:0xf
	v_mul_f32_dpp v90, v90, v90 row_bcast:15 row_mask:0xa bank_mask:0xf
	v_mul_f32_dpp v91, v91, v91 row_bcast:15 row_mask:0xa bank_mask:0xf
	ds_read_b128 v[0:3], v234 offset:39296
	v_exp_f32_e32 v8, v8
	v_exp_f32_e32 v9, v9
	v_exp_f32_e32 v10, v10
	v_exp_f32_e32 v11, v11
	v_exp_f32_e32 v24, v24
	v_exp_f32_e32 v25, v25
	v_exp_f32_e32 v26, v26
	v_exp_f32_e32 v27, v27
	v_pk_add_f32 v[8:9], v[8:9], v[240:241] op_sel_hi:[1,0]
	v_pk_add_f32 v[10:11], v[10:11], v[240:241] op_sel_hi:[1,0]
	v_pk_add_f32 v[24:25], v[24:25], v[240:241] op_sel_hi:[1,0]
	v_pk_add_f32 v[26:27], v[26:27], v[240:241] op_sel_hi:[1,0]
	v_rcp_f32_e32 v8, v8
	v_rcp_f32_e32 v9, v9
	v_rcp_f32_e32 v10, v10
	v_rcp_f32_e32 v11, v11
	v_rcp_f32_e32 v24, v24
	v_rcp_f32_e32 v25, v25
	v_rcp_f32_e32 v26, v26
	v_rcp_f32_e32 v27, v27
	v_mul_f32_e32 v200, v97, v24
	v_mul_f32_e32 v201, v98, v25
	v_mul_f32_e32 v202, v102, v26
	v_mul_f32_e32 v203, v103, v27
	s_waitcnt lgkmcnt(0)
	v_pk_mul_f32 v[8:9], v[8:9], v[0:1]
	v_pk_mul_f32 v[10:11], v[10:11], v[2:3]
	v_pk_mul_f32 v[204:205], v[8:9], v[242:243] op_sel_hi:[1,0]
	v_pk_mul_f32 v[206:207], v[10:11], v[242:243] op_sel_hi:[1,0]
	v_exp_f32_e32 v96, v8
	v_exp_f32_e32 v97, v9
	v_exp_f32_e32 v98, v10
	v_exp_f32_e32 v99, v11
	v_pk_fma_f32 v[208:209], v[204:205], v[244:245], v[238:239] op_sel_hi:[1,0,0]
	v_pk_fma_f32 v[210:211], v[206:207], v[244:245], v[238:239] op_sel_hi:[1,0,0]
	v_pk_fma_f32 v[208:209], v[204:205], v[208:209], v[246:247] op_sel_hi:[1,1,0]
	v_pk_fma_f32 v[210:211], v[206:207], v[210:211], v[246:247] op_sel_hi:[1,1,0]
	v_pk_fma_f32 v[208:209], v[204:205], v[208:209], v[248:249] op_sel_hi:[1,1,0]
	v_pk_fma_f32 v[210:211], v[206:207], v[210:211], v[248:249] op_sel_hi:[1,1,0]
	v_pk_fma_f32 v[208:209], v[204:205], v[208:209], v[240:241] op_sel_hi:[1,1,0]
	v_pk_fma_f32 v[210:211], v[206:207], v[210:211], v[240:241] op_sel_hi:[1,1,0]
	v_pk_mul_f32 v[208:209], v[208:209], v[204:205] neg_lo:[0,1] neg_hi:[0,1]
	v_pk_mul_f32 v[210:211], v[210:211], v[206:207] neg_lo:[0,1] neg_hi:[0,1]
	v_pk_fma_f32 v[212:213], v[96:97], v[96:97], v[240:241] op_sel_hi:[1,1,0] neg_lo:[1,0,0] neg_hi:[1,0,0]
	v_pk_fma_f32 v[214:215], v[98:99], v[98:99], v[240:241] op_sel_hi:[1,1,0] neg_lo:[1,0,0] neg_hi:[1,0,0]
	v_cmp_lt_f32_e64 s[70:71], s29, v204
	v_cmp_lt_f32_e64 s[72:73], s29, v205
	v_cmp_lt_f32_e64 s[74:75], s29, v206
	v_cmp_lt_f32_e64 s[76:77], s29, v207
	v_cndmask_b32_e64 v212, v212, v208, s[70:71]
	v_cndmask_b32_e64 v213, v213, v209, s[72:73]
	v_cndmask_b32_e64 v214, v214, v210, s[74:75]
	v_cndmask_b32_e64 v215, v215, v211, s[76:77]
	v_sqrt_f32_e32 v212, v212
	v_sqrt_f32_e32 v213, v213
	v_sqrt_f32_e32 v214, v214
	v_sqrt_f32_e32 v215, v215
	v_pk_mul_f32 v[100:101], v[200:201], v[212:213]
	v_pk_mul_f32 v[102:103], v[202:203], v[214:215]
	s_nop 1
	v_fmac_f32_dpp v100, v100, v96 row_shr:1 row_mask:0xf bank_mask:0xf
	v_fmac_f32_dpp v101, v101, v97 row_shr:1 row_mask:0xf bank_mask:0xf
	v_fmac_f32_dpp v102, v102, v98 row_shr:1 row_mask:0xf bank_mask:0xf
	v_fmac_f32_dpp v103, v103, v99 row_shr:1 row_mask:0xf bank_mask:0xf
	v_mul_f32_dpp v96, v96, v96 row_shr:1 row_mask:0xf bank_mask:0xf
	v_mul_f32_dpp v97, v97, v97 row_shr:1 row_mask:0xf bank_mask:0xf
	v_mul_f32_dpp v98, v98, v98 row_shr:1 row_mask:0xf bank_mask:0xf
	v_mul_f32_dpp v99, v99, v99 row_shr:1 row_mask:0xf bank_mask:0xf
	v_fmac_f32_dpp v100, v100, v96 row_shr:2 row_mask:0xf bank_mask:0xf
	v_fmac_f32_dpp v101, v101, v97 row_shr:2 row_mask:0xf bank_mask:0xf
	v_fmac_f32_dpp v102, v102, v98 row_shr:2 row_mask:0xf bank_mask:0xf
	v_fmac_f32_dpp v103, v103, v99 row_shr:2 row_mask:0xf bank_mask:0xf
	v_mul_f32_dpp v96, v96, v96 row_shr:2 row_mask:0xf bank_mask:0xf
	v_mul_f32_dpp v97, v97, v97 row_shr:2 row_mask:0xf bank_mask:0xf
	v_mul_f32_dpp v98, v98, v98 row_shr:2 row_mask:0xf bank_mask:0xf
	v_mul_f32_dpp v99, v99, v99 row_shr:2 row_mask:0xf bank_mask:0xf
	v_fmac_f32_dpp v100, v100, v96 row_shr:4 row_mask:0xf bank_mask:0xf
	v_fmac_f32_dpp v101, v101, v97 row_shr:4 row_mask:0xf bank_mask:0xf
	v_fmac_f32_dpp v102, v102, v98 row_shr:4 row_mask:0xf bank_mask:0xf
	v_fmac_f32_dpp v103, v103, v99 row_shr:4 row_mask:0xf bank_mask:0xf
	v_mul_f32_dpp v96, v96, v96 row_shr:4 row_mask:0xf bank_mask:0xf
	v_mul_f32_dpp v97, v97, v97 row_shr:4 row_mask:0xf bank_mask:0xf
	v_mul_f32_dpp v98, v98, v98 row_shr:4 row_mask:0xf bank_mask:0xf
	v_mul_f32_dpp v99, v99, v99 row_shr:4 row_mask:0xf bank_mask:0xf
	v_fmac_f32_dpp v100, v100, v96 row_shr:8 row_mask:0xf bank_mask:0xf
	v_fmac_f32_dpp v101, v101, v97 row_shr:8 row_mask:0xf bank_mask:0xf
	v_fmac_f32_dpp v102, v102, v98 row_shr:8 row_mask:0xf bank_mask:0xf
	v_fmac_f32_dpp v103, v103, v99 row_shr:8 row_mask:0xf bank_mask:0xf
	v_mul_f32_dpp v96, v96, v96 row_shr:8 row_mask:0xf bank_mask:0xf
	v_mul_f32_dpp v97, v97, v97 row_shr:8 row_mask:0xf bank_mask:0xf
	v_mul_f32_dpp v98, v98, v98 row_shr:8 row_mask:0xf bank_mask:0xf
	v_mul_f32_dpp v99, v99, v99 row_shr:8 row_mask:0xf bank_mask:0xf
	v_fmac_f32_dpp v100, v100, v96 row_bcast:15 row_mask:0xa bank_mask:0xf
	v_fmac_f32_dpp v101, v101, v97 row_bcast:15 row_mask:0xa bank_mask:0xf
	v_fmac_f32_dpp v102, v102, v98 row_bcast:15 row_mask:0xa bank_mask:0xf
	v_fmac_f32_dpp v103, v103, v99 row_bcast:15 row_mask:0xa bank_mask:0xf
	v_mul_f32_dpp v96, v96, v96 row_bcast:15 row_mask:0xa bank_mask:0xf
	v_mul_f32_dpp v97, v97, v97 row_bcast:15 row_mask:0xa bank_mask:0xf
	v_mul_f32_dpp v98, v98, v98 row_bcast:15 row_mask:0xa bank_mask:0xf
	v_mul_f32_dpp v99, v99, v99 row_bcast:15 row_mask:0xa bank_mask:0xf
	ds_read_b128 v[0:3], v234 offset:39328
	v_exp_f32_e32 v12, v12
	v_exp_f32_e32 v13, v13
	v_exp_f32_e32 v14, v14
	v_exp_f32_e32 v15, v15
	v_exp_f32_e32 v28, v28
	v_exp_f32_e32 v29, v29
	v_exp_f32_e32 v30, v30
	v_exp_f32_e32 v31, v31
	v_pk_add_f32 v[12:13], v[12:13], v[240:241] op_sel_hi:[1,0]
	v_pk_add_f32 v[14:15], v[14:15], v[240:241] op_sel_hi:[1,0]
	v_pk_add_f32 v[28:29], v[28:29], v[240:241] op_sel_hi:[1,0]
	v_pk_add_f32 v[30:31], v[30:31], v[240:241] op_sel_hi:[1,0]
	v_rcp_f32_e32 v12, v12
	v_rcp_f32_e32 v13, v13
	v_rcp_f32_e32 v14, v14
	v_rcp_f32_e32 v15, v15
	v_rcp_f32_e32 v28, v28
	v_rcp_f32_e32 v29, v29
	v_rcp_f32_e32 v30, v30
	v_rcp_f32_e32 v31, v31
	v_mul_f32_e32 v200, v105, v28
	v_mul_f32_e32 v201, v106, v29
	v_mul_f32_e32 v202, v110, v30
	v_mul_f32_e32 v203, v111, v31
	s_waitcnt lgkmcnt(0)
; #define LAS __attribute__((address_space(3)))
; __device__ __forceinline__ float ex2(float x) { return __builtin_amdgcn_exp2f(x); }
; __device__ __forceinline__ float rcpf_(float x) { return __builtin_amdgcn_rcpf(x); }
; __device__ __forceinline__ void lru_phase(const Ptrs& P, LAS unsigned char* lds, int G, int wave, int lane, int tid) {
;     ...
; #pragma unroll
;             for (int i4 = 0; i4 < 4; ++i4) { if (mt == 2 && i4 >= 2) continue;
;                 const int s = 2 * mt + (i4 >> 1), half = i4 & 1, ch0 = 16 * s + 8 * half + 4 * hh;
;                 const f32x4 ls2 = *(const LAS f32x4*)(par + 7 * LB + ch0);
;                 float A4[4], B4[4];
; #pragma unroll
;                 for (int q = 0; q < 4; ++q) { const int i = 4 * i4 + q;
;                     const float rg = rcpf_(1.0f + ex2(gr[i])), ig = rcpf_(1.0f + ex2(gi[i]));
;                     const float la2 = ls2[q] * rg, a = ex2(la2), xx = (2.0f * LN2) * la2;
;                     const float poly = -xx * (1.0f + xx * (0.5f + xx * ((1.0f / 6.0f) + xx * ((1.0f / 24.0f) + xx * (1.0f / 120.0f)))));
;                     const float om = (xx > -0.25f) ? poly : (1.0f - a * a);
;                     A4[q] = a; B4[q] = __builtin_amdgcn_sqrtf(om) * (ig * xc[s][half][q]); }
;                 asm volatile("s_nop 1\n\t"
;                     LRU_DPP4("row_shr:1 row_mask:0xf bank_mask:0xf") LRU_DPP4("row_shr:2 row_mask:0xf bank_mask:0xf") LRU_DPP4("row_shr:4 row_mask:0xf bank_mask:0xf")
;                     LRU_DPP4("row_shr:8 row_mask:0xf bank_mask:0xf") LRU_DPP4("row_bcast:15 row_mask:0xa bank_mask:0xf")
;                     : "+v"(A4[0]), "+v"(A4[1]), "+v"(A4[2]), "+v"(A4[3]), "+v"(B4[0]), "+v"(B4[1]), "+v"(B4[2]), "+v"(B4[3]));
; #pragma unroll
;                 for (int q = 0; q < 4; ++q) { Av[s][half][q] = A4[q]; xc[s][half][q] = B4[q]; }
;                 __builtin_amdgcn_sched_barrier(0); }
	v_pk_mul_f32 v[12:13], v[12:13], v[0:1]
	v_pk_mul_f32 v[14:15], v[14:15], v[2:3]
	v_pk_mul_f32 v[204:205], v[12:13], v[242:243] op_sel_hi:[1,0]
	v_pk_mul_f32 v[206:207], v[14:15], v[242:243] op_sel_hi:[1,0]
	v_exp_f32_e32 v104, v12
	v_exp_f32_e32 v105, v13
	v_exp_f32_e32 v106, v14
	v_exp_f32_e32 v107, v15
	v_pk_fma_f32 v[208:209], v[204:205], v[244:245], v[238:239] op_sel_hi:[1,0,0]
	v_pk_fma_f32 v[210:211], v[206:207], v[244:245], v[238:239] op_sel_hi:[1,0,0]
	v_pk_fma_f32 v[208:209], v[204:205], v[208:209], v[246:247] op_sel_hi:[1,1,0]
	v_pk_fma_f32 v[210:211], v[206:207], v[210:211], v[246:247] op_sel_hi:[1,1,0]
	v_pk_fma_f32 v[208:209], v[204:205], v[208:209], v[248:249] op_sel_hi:[1,1,0]
	v_pk_fma_f32 v[210:211], v[206:207], v[210:211], v[248:249] op_sel_hi:[1,1,0]
	v_pk_fma_f32 v[208:209], v[204:205], v[208:209], v[240:241] op_sel_hi:[1,1,0]
	v_pk_fma_f32 v[210:211], v[206:207], v[210:211], v[240:241] op_sel_hi:[1,1,0]
	v_pk_mul_f32 v[208:209], v[208:209], v[204:205] neg_lo:[0,1] neg_hi:[0,1]
	v_pk_mul_f32 v[210:211], v[210:211], v[206:207] neg_lo:[0,1] neg_hi:[0,1]
	v_pk_fma_f32 v[212:213], v[104:105], v[104:105], v[240:241] op_sel_hi:[1,1,0] neg_lo:[1,0,0] neg_hi:[1,0,0]
	v_pk_fma_f32 v[214:215], v[106:107], v[106:107], v[240:241] op_sel_hi:[1,1,0] neg_lo:[1,0,0] neg_hi:[1,0,0]
	v_cmp_lt_f32_e64 s[70:71], s29, v204
	v_cmp_lt_f32_e64 s[72:73], s29, v205
	v_cmp_lt_f32_e64 s[74:75], s29, v206
	v_cmp_lt_f32_e64 s[76:77], s29, v207
	v_cndmask_b32_e64 v212, v212, v208, s[70:71]
	v_cndmask_b32_e64 v213, v213, v209, s[72:73]
	v_cndmask_b32_e64 v214, v214, v210, s[74:75]
	v_cndmask_b32_e64 v215, v215, v211, s[76:77]
	v_sqrt_f32_e32 v212, v212
	v_sqrt_f32_e32 v213, v213
	v_sqrt_f32_e32 v214, v214
	v_sqrt_f32_e32 v215, v215
	v_pk_mul_f32 v[108:109], v[200:201], v[212:213]
	v_pk_mul_f32 v[110:111], v[202:203], v[214:215]
	s_nop 1
	v_fmac_f32_dpp v108, v108, v104 row_shr:1 row_mask:0xf bank_mask:0xf
	v_fmac_f32_dpp v109, v109, v105 row_shr:1 row_mask:0xf bank_mask:0xf
	v_fmac_f32_dpp v110, v110, v106 row_shr:1 row_mask:0xf bank_mask:0xf
	v_fmac_f32_dpp v111, v111, v107 row_shr:1 row_mask:0xf bank_mask:0xf
	v_mul_f32_dpp v104, v104, v104 row_shr:1 row_mask:0xf bank_mask:0xf
	v_mul_f32_dpp v105, v105, v105 row_shr:1 row_mask:0xf bank_mask:0xf
	v_mul_f32_dpp v106, v106, v106 row_shr:1 row_mask:0xf bank_mask:0xf
	v_mul_f32_dpp v107, v107, v107 row_shr:1 row_mask:0xf bank_mask:0xf
	v_fmac_f32_dpp v108, v108, v104 row_shr:2 row_mask:0xf bank_mask:0xf
	v_fmac_f32_dpp v109, v109, v105 row_shr:2 row_mask:0xf bank_mask:0xf
	v_fmac_f32_dpp v110, v110, v106 row_shr:2 row_mask:0xf bank_mask:0xf
	v_fmac_f32_dpp v111, v111, v107 row_shr:2 row_mask:0xf bank_mask:0xf
	v_mul_f32_dpp v104, v104, v104 row_shr:2 row_mask:0xf bank_mask:0xf
	v_mul_f32_dpp v105, v105, v105 row_shr:2 row_mask:0xf bank_mask:0xf
	v_mul_f32_dpp v106, v106, v106 row_shr:2 row_mask:0xf bank_mask:0xf
	v_mul_f32_dpp v107, v107, v107 row_shr:2 row_mask:0xf bank_mask:0xf
	v_fmac_f32_dpp v108, v108, v104 row_shr:4 row_mask:0xf bank_mask:0xf
	v_fmac_f32_dpp v109, v109, v105 row_shr:4 row_mask:0xf bank_mask:0xf
	v_fmac_f32_dpp v110, v110, v106 row_shr:4 row_mask:0xf bank_mask:0xf
	v_fmac_f32_dpp v111, v111, v107 row_shr:4 row_mask:0xf bank_mask:0xf
	v_mul_f32_dpp v104, v104, v104 row_shr:4 row_mask:0xf bank_mask:0xf
	v_mul_f32_dpp v105, v105, v105 row_shr:4 row_mask:0xf bank_mask:0xf
	v_mul_f32_dpp v106, v106, v106 row_shr:4 row_mask:0xf bank_mask:0xf
	v_mul_f32_dpp v107, v107, v107 row_shr:4 row_mask:0xf bank_mask:0xf
	v_fmac_f32_dpp v108, v108, v104 row_shr:8 row_mask:0xf bank_mask:0xf
	v_fmac_f32_dpp v109, v109, v105 row_shr:8 row_mask:0xf bank_mask:0xf
	v_fmac_f32_dpp v110, v110, v106 row_shr:8 row_mask:0xf bank_mask:0xf
	v_fmac_f32_dpp v111, v111, v107 row_shr:8 row_mask:0xf bank_mask:0xf
	v_mul_f32_dpp v104, v104, v104 row_shr:8 row_mask:0xf bank_mask:0xf
	v_mul_f32_dpp v105, v105, v105 row_shr:8 row_mask:0xf bank_mask:0xf
	v_mul_f32_dpp v106, v106, v106 row_shr:8 row_mask:0xf bank_mask:0xf
	v_mul_f32_dpp v107, v107, v107 row_shr:8 row_mask:0xf bank_mask:0xf
	v_fmac_f32_dpp v108, v108, v104 row_bcast:15 row_mask:0xa bank_mask:0xf
	v_fmac_f32_dpp v109, v109, v105 row_bcast:15 row_mask:0xa bank_mask:0xf
	v_fmac_f32_dpp v110, v110, v106 row_bcast:15 row_mask:0xa bank_mask:0xf
	v_fmac_f32_dpp v111, v111, v107 row_bcast:15 row_mask:0xa bank_mask:0xf
	v_mul_f32_dpp v104, v104, v104 row_bcast:15 row_mask:0xa bank_mask:0xf
	v_mul_f32_dpp v105, v105, v105 row_bcast:15 row_mask:0xa bank_mask:0xf
	v_mul_f32_dpp v106, v106, v106 row_bcast:15 row_mask:0xa bank_mask:0xf
	v_mul_f32_dpp v107, v107, v107 row_bcast:15 row_mask:0xa bank_mask:0xf

; #define LAS __attribute__((address_space(3)))
; __device__ __forceinline__ void lru_phase(const Ptrs& P, LAS unsigned char* lds, int G, int wave, int lane, int tid) {
;     ...
;         for (int mt = 0; mt < 3; ++mt) {
;             f32x16 gr, gi;
; #pragma unroll
;             for (int i = 0; i < 16; ++i) { gr[i] = 0.f; gi[i] = 0.f; }
;             const LAS bf16x8* wa = (const LAS bf16x8*)(lds + L_WGF) + (size_t)(mt * 6) * 64 + lane;
;             const LAS bf16x8* wb = (const LAS bf16x8*)(lds + L_WGF) + (size_t)((3 + mt) * 6) * 64 + lane;
; #pragma unroll
;             for (int s = 0; s < 5; ++s) { gr = MFMA32(wa[s * 64], xf[s], gr); gi = MFMA32(wb[s * 64], xf[s], gi); }
;             gr = MFMA32(wa[5 * 64], xone, gr); gi = MFMA32(wb[5 * 64], xone, gi);
;             __builtin_amdgcn_sched_barrier(0);
; #pragma unroll
;             for (int i4 = 0; i4 < 4; ++i4) { if (mt == 2 && i4 >= 2) continue;
;                 const int s = 2 * mt + (i4 >> 1), half = i4 & 1, ch0 = 16 * s + 8 * half + 4 * hh;
;                 const f32x4 ls2 = *(const LAS f32x4*)(par + 7 * LB + ch0);
;                 float A4[4], B4[4];
; #pragma unroll
;                 for (int q = 0; q < 4; ++q) { const int i = 4 * i4 + q;
;                     const float rg = rcpf_(1.0f + ex2(gr[i])), ig = rcpf_(1.0f + ex2(gi[i]));
;                     const float la2 = ls2[q] * rg, a = ex2(la2), xx = (2.0f * LN2) * la2;
;                     const float poly = -xx * (1.0f + xx * (0.5f + xx * ((1.0f / 6.0f) + xx * ((1.0f / 24.0f) + xx * (1.0f / 120.0f)))));
;                     const float om = (xx > -0.25f) ? poly : (1.0f - a * a);
;                     A4[q] = a; B4[q] = __builtin_amdgcn_sqrtf(om) * (ig * xc[s][half][q]); }
;                 asm volatile("s_nop 1\n\t"
;                     LRU_DPP4("row_shr:1 row_mask:0xf bank_mask:0xf") LRU_DPP4("row_shr:2 row_mask:0xf bank_mask:0xf") LRU_DPP4("row_shr:4 row_mask:0xf bank_mask:0xf")
;                     LRU_DPP4("row_shr:8 row_mask:0xf bank_mask:0xf") LRU_DPP4("row_bcast:15 row_mask:0xa bank_mask:0xf")
;                     : "+v"(A4[0]), "+v"(A4[1]), "+v"(A4[2]), "+v"(A4[3]), "+v"(B4[0]), "+v"(B4[1]), "+v"(B4[2]), "+v"(B4[3]));
; #pragma unroll
;                 for (int q = 0; q < 4; ++q) { Av[s][half][q] = A4[q]; xc[s][half][q] = B4[q]; }
;                 __builtin_amdgcn_sched_barrier(0); }
	ds_read_b128 v[0:3], v237 offset:12288
	ds_read_b128 v[140:143], v237 offset:13312
	ds_read_b128 v[16:19], v237 offset:30720
	ds_read_b128 v[144:147], v237 offset:31744
	s_waitcnt lgkmcnt(3)
	v_mfma_f32_32x32x16_bf16 v[0:15], v[0:3], v[36:39], 0
	s_waitcnt lgkmcnt(1)
	v_mfma_f32_32x32x16_bf16 v[16:31], v[16:19], v[36:39], 0
	v_mfma_f32_32x32x16_bf16 v[0:15], v[140:143], v[40:43], v[0:15]
	s_waitcnt lgkmcnt(0)
	v_mfma_f32_32x32x16_bf16 v[16:31], v[144:147], v[40:43], v[16:31]
	ds_read_b128 v[36:39], v237 offset:14336
	ds_read_b128 v[40:43], v237 offset:15360
	s_waitcnt lgkmcnt(1)
	v_mfma_f32_32x32x16_bf16 v[0:15], v[36:39], v[76:79], v[0:15]
	ds_read_b128 v[36:39], v237 offset:32768
	ds_read_b128 v[140:143], v237 offset:33792
	s_waitcnt lgkmcnt(1)
	v_mfma_f32_32x32x16_bf16 v[16:31], v[36:39], v[76:79], v[16:31]
	v_mfma_f32_32x32x16_bf16 v[0:15], v[40:43], v[112:115], v[0:15]
	ds_read_b128 v[36:39], v237 offset:16384
	ds_read_b128 v[40:43], v237 offset:17408
	s_waitcnt lgkmcnt(2)
	v_mfma_f32_32x32x16_bf16 v[16:31], v[140:143], v[112:115], v[16:31]
	s_waitcnt lgkmcnt(1)
	v_mfma_f32_32x32x16_bf16 v[0:15], v[36:39], v[124:127], v[0:15]
	ds_read_b128 v[36:39], v237 offset:34816
	ds_read_b128 v[76:79], v237 offset:35840
	s_waitcnt lgkmcnt(1)
	v_mfma_f32_32x32x16_bf16 v[16:31], v[36:39], v[124:127], v[16:31]
	v_mfma_f32_32x32x16_bf16 v[0:15], v[40:43], v[32:35], v[0:15]
	s_waitcnt lgkmcnt(0)
	v_mfma_f32_32x32x16_bf16 v[16:31], v[76:79], v[32:35], v[16:31]
	s_nop 9
	ds_read_b128 v[8:11], v234 offset:39360
	v_exp_f32_e32 v0, v0
	v_exp_f32_e32 v1, v1
	v_exp_f32_e32 v2, v2
	v_exp_f32_e32 v3, v3
	v_exp_f32_e32 v16, v16
	v_exp_f32_e32 v17, v17
	v_exp_f32_e32 v18, v18
	v_exp_f32_e32 v19, v19
	v_pk_add_f32 v[0:1], v[0:1], v[240:241] op_sel_hi:[1,0]
	v_pk_add_f32 v[2:3], v[2:3], v[240:241] op_sel_hi:[1,0]
	v_pk_add_f32 v[16:17], v[16:17], v[240:241] op_sel_hi:[1,0]
	v_pk_add_f32 v[18:19], v[18:19], v[240:241] op_sel_hi:[1,0]
	v_rcp_f32_e32 v0, v0
	v_rcp_f32_e32 v1, v1
	v_rcp_f32_e32 v2, v2
	v_rcp_f32_e32 v3, v3
	v_rcp_f32_e32 v16, v16
	v_rcp_f32_e32 v17, v17
	v_rcp_f32_e32 v18, v18
	v_rcp_f32_e32 v19, v19
	v_mul_f32_e32 v200, v136, v16
	v_mul_f32_e32 v201, v129, v17
	v_mul_f32_e32 v202, v116, v18
	v_mul_f32_e32 v203, v119, v19
	s_waitcnt lgkmcnt(0)
	v_pk_mul_f32 v[0:1], v[0:1], v[8:9]
	v_pk_mul_f32 v[2:3], v[2:3], v[10:11]
	v_pk_mul_f32 v[204:205], v[0:1], v[242:243] op_sel_hi:[1,0]
	v_pk_mul_f32 v[206:207], v[2:3], v[242:243] op_sel_hi:[1,0]
	v_exp_f32_e32 v0, v0
	v_exp_f32_e32 v1, v1
	v_exp_f32_e32 v2, v2
	v_exp_f32_e32 v3, v3
	v_pk_fma_f32 v[208:209], v[204:205], v[244:245], v[238:239] op_sel_hi:[1,0,0]
	v_pk_fma_f32 v[210:211], v[206:207], v[244:245], v[238:239] op_sel_hi:[1,0,0]
	v_pk_fma_f32 v[208:209], v[204:205], v[208:209], v[246:247] op_sel_hi:[1,1,0]
	v_pk_fma_f32 v[210:211], v[206:207], v[210:211], v[246:247] op_sel_hi:[1,1,0]
	v_pk_fma_f32 v[208:209], v[204:205], v[208:209], v[248:249] op_sel_hi:[1,1,0]
	v_pk_fma_f32 v[210:211], v[206:207], v[210:211], v[248:249] op_sel_hi:[1,1,0]
	v_pk_fma_f32 v[208:209], v[204:205], v[208:209], v[240:241] op_sel_hi:[1,1,0]
	v_pk_fma_f32 v[210:211], v[206:207], v[210:211], v[240:241] op_sel_hi:[1,1,0]
	v_pk_mul_f32 v[208:209], v[208:209], v[204:205] neg_lo:[0,1] neg_hi:[0,1]
	v_pk_mul_f32 v[210:211], v[210:211], v[206:207] neg_lo:[0,1] neg_hi:[0,1]
	v_pk_fma_f32 v[212:213], v[0:1], v[0:1], v[240:241] op_sel_hi:[1,1,0] neg_lo:[1,0,0] neg_hi:[1,0,0]
	v_pk_fma_f32 v[214:215], v[2:3], v[2:3], v[240:241] op_sel_hi:[1,1,0] neg_lo:[1,0,0] neg_hi:[1,0,0]
	v_cmp_lt_f32_e64 s[70:71], s29, v204
	v_cmp_lt_f32_e64 s[72:73], s29, v205
	v_cmp_lt_f32_e64 s[74:75], s29, v206
	v_cmp_lt_f32_e64 s[76:77], s29, v207
	v_cndmask_b32_e64 v212, v212, v208, s[70:71]
	v_cndmask_b32_e64 v213, v213, v209, s[72:73]
	v_cndmask_b32_e64 v214, v214, v210, s[74:75]
	v_cndmask_b32_e64 v215, v215, v211, s[76:77]
	v_sqrt_f32_e32 v212, v212
	v_sqrt_f32_e32 v213, v213
	v_sqrt_f32_e32 v214, v214
	v_sqrt_f32_e32 v215, v215
	v_pk_mul_f32 v[8:9], v[200:201], v[212:213]
	v_pk_mul_f32 v[10:11], v[202:203], v[214:215]
	s_nop 1
	v_fmac_f32_dpp v8, v8, v0 row_shr:1 row_mask:0xf bank_mask:0xf
	v_fmac_f32_dpp v9, v9, v1 row_shr:1 row_mask:0xf bank_mask:0xf
	v_fmac_f32_dpp v10, v10, v2 row_shr:1 row_mask:0xf bank_mask:0xf
	v_fmac_f32_dpp v11, v11, v3 row_shr:1 row_mask:0xf bank_mask:0xf
	v_mul_f32_dpp v0, v0, v0 row_shr:1 row_mask:0xf bank_mask:0xf
	v_mul_f32_dpp v1, v1, v1 row_shr:1 row_mask:0xf bank_mask:0xf
	v_mul_f32_dpp v2, v2, v2 row_shr:1 row_mask:0xf bank_mask:0xf
	v_mul_f32_dpp v3, v3, v3 row_shr:1 row_mask:0xf bank_mask:0xf
	v_fmac_f32_dpp v8, v8, v0 row_shr:2 row_mask:0xf bank_mask:0xf
	v_fmac_f32_dpp v9, v9, v1 row_shr:2 row_mask:0xf bank_mask:0xf
	v_fmac_f32_dpp v10, v10, v2 row_shr:2 row_mask:0xf bank_mask:0xf
	v_fmac_f32_dpp v11, v11, v3 row_shr:2 row_mask:0xf bank_mask:0xf
	v_mul_f32_dpp v0, v0, v0 row_shr:2 row_mask:0xf bank_mask:0xf
	v_mul_f32_dpp v1, v1, v1 row_shr:2 row_mask:0xf bank_mask:0xf
	v_mul_f32_dpp v2, v2, v2 row_shr:2 row_mask:0xf bank_mask:0xf
	v_mul_f32_dpp v3, v3, v3 row_shr:2 row_mask:0xf bank_mask:0xf
	v_fmac_f32_dpp v8, v8, v0 row_shr:4 row_mask:0xf bank_mask:0xf
	v_fmac_f32_dpp v9, v9, v1 row_shr:4 row_mask:0xf bank_mask:0xf
	v_fmac_f32_dpp v10, v10, v2 row_shr:4 row_mask:0xf bank_mask:0xf
	v_fmac_f32_dpp v11, v11, v3 row_shr:4 row_mask:0xf bank_mask:0xf
	v_mul_f32_dpp v0, v0, v0 row_shr:4 row_mask:0xf bank_mask:0xf
	v_mul_f32_dpp v1, v1, v1 row_shr:4 row_mask:0xf bank_mask:0xf
	v_mul_f32_dpp v2, v2, v2 row_shr:4 row_mask:0xf bank_mask:0xf
	v_mul_f32_dpp v3, v3, v3 row_shr:4 row_mask:0xf bank_mask:0xf
; #define LAS __attribute__((address_space(3)))
; __device__ __forceinline__ float ex2(float x) { return __builtin_amdgcn_exp2f(x); }
; __device__ __forceinline__ float rcpf_(float x) { return __builtin_amdgcn_rcpf(x); }
; __device__ __forceinline__ void lru_phase(const Ptrs& P, LAS unsigned char* lds, int G, int wave, int lane, int tid) {
;     ...
; #pragma unroll
;             for (int i4 = 0; i4 < 4; ++i4) { if (mt == 2 && i4 >= 2) continue;
;                 const int s = 2 * mt + (i4 >> 1), half = i4 & 1, ch0 = 16 * s + 8 * half + 4 * hh;
;                 const f32x4 ls2 = *(const LAS f32x4*)(par + 7 * LB + ch0);
;                 float A4[4], B4[4];
; #pragma unroll
;                 for (int q = 0; q < 4; ++q) { const int i = 4 * i4 + q;
;                     const float rg = rcpf_(1.0f + ex2(gr[i])), ig = rcpf_(1.0f + ex2(gi[i]));
;                     const float la2 = ls2[q] * rg, a = ex2(la2), xx = (2.0f * LN2) * la2;
;                     const float poly = -xx * (1.0f + xx * (0.5f + xx * ((1.0f / 6.0f) + xx * ((1.0f / 24.0f) + xx * (1.0f / 120.0f)))));
;                     const float om = (xx > -0.25f) ? poly : (1.0f - a * a);
;                     A4[q] = a; B4[q] = __builtin_amdgcn_sqrtf(om) * (ig * xc[s][half][q]); }
;                 asm volatile("s_nop 1\n\t"
;                     LRU_DPP4("row_shr:1 row_mask:0xf bank_mask:0xf") LRU_DPP4("row_shr:2 row_mask:0xf bank_mask:0xf") LRU_DPP4("row_shr:4 row_mask:0xf bank_mask:0xf")
;                     LRU_DPP4("row_shr:8 row_mask:0xf bank_mask:0xf") LRU_DPP4("row_bcast:15 row_mask:0xa bank_mask:0xf")
;                     : "+v"(A4[0]), "+v"(A4[1]), "+v"(A4[2]), "+v"(A4[3]), "+v"(B4[0]), "+v"(B4[1]), "+v"(B4[2]), "+v"(B4[3]));
; #pragma unroll
;                 for (int q = 0; q < 4; ++q) { Av[s][half][q] = A4[q]; xc[s][half][q] = B4[q]; }
;                 __builtin_amdgcn_sched_barrier(0); }
	v_fmac_f32_dpp v8, v8, v0 row_shr:8 row_mask:0xf bank_mask:0xf
	v_fmac_f32_dpp v9, v9, v1 row_shr:8 row_mask:0xf bank_mask:0xf
	v_fmac_f32_dpp v10, v10, v2 row_shr:8 row_mask:0xf bank_mask:0xf
	v_fmac_f32_dpp v11, v11, v3 row_shr:8 row_mask:0xf bank_mask:0xf
	v_mul_f32_dpp v0, v0, v0 row_shr:8 row_mask:0xf bank_mask:0xf
	v_mul_f32_dpp v1, v1, v1 row_shr:8 row_mask:0xf bank_mask:0xf
	v_mul_f32_dpp v2, v2, v2 row_shr:8 row_mask:0xf bank_mask:0xf
	v_mul_f32_dpp v3, v3, v3 row_shr:8 row_mask:0xf bank_mask:0xf
	v_fmac_f32_dpp v8, v8, v0 row_bcast:15 row_mask:0xa bank_mask:0xf
	v_fmac_f32_dpp v9, v9, v1 row_bcast:15 row_mask:0xa bank_mask:0xf
	v_fmac_f32_dpp v10, v10, v2 row_bcast:15 row_mask:0xa bank_mask:0xf
	v_fmac_f32_dpp v11, v11, v3 row_bcast:15 row_mask:0xa bank_mask:0xf
	v_mul_f32_dpp v0, v0, v0 row_bcast:15 row_mask:0xa bank_mask:0xf
	v_mul_f32_dpp v1, v1, v1 row_bcast:15 row_mask:0xa bank_mask:0xf
	v_mul_f32_dpp v2, v2, v2 row_bcast:15 row_mask:0xa bank_mask:0xf
	v_mul_f32_dpp v3, v3, v3 row_bcast:15 row_mask:0xa bank_mask:0xf
	ds_read_b128 v[12:15], v234 offset:39392
	v_exp_f32_e32 v4, v4
	v_exp_f32_e32 v5, v5
	v_exp_f32_e32 v6, v6
	v_exp_f32_e32 v7, v7
	v_exp_f32_e32 v20, v20
	v_exp_f32_e32 v21, v21
	v_exp_f32_e32 v22, v22
	v_exp_f32_e32 v23, v23
	v_pk_add_f32 v[4:5], v[4:5], v[240:241] op_sel_hi:[1,0]
	v_pk_add_f32 v[6:7], v[6:7], v[240:241] op_sel_hi:[1,0]
	v_pk_add_f32 v[20:21], v[20:21], v[240:241] op_sel_hi:[1,0]
	v_pk_add_f32 v[22:23], v[22:23], v[240:241] op_sel_hi:[1,0]
	v_rcp_f32_e32 v4, v4
	v_rcp_f32_e32 v5, v5
	v_rcp_f32_e32 v6, v6
	v_rcp_f32_e32 v7, v7
	v_rcp_f32_e32 v20, v20
	v_rcp_f32_e32 v21, v21
	v_rcp_f32_e32 v22, v22
	v_rcp_f32_e32 v23, v23
	v_mul_f32_e32 v200, v120, v20
	v_mul_f32_e32 v201, v118, v21
	v_mul_f32_e32 v202, v117, v22
	v_mul_f32_e32 v203, v123, v23
	s_waitcnt lgkmcnt(0)
	v_pk_mul_f32 v[4:5], v[4:5], v[12:13]
	v_pk_mul_f32 v[6:7], v[6:7], v[14:15]
	v_pk_mul_f32 v[204:205], v[4:5], v[242:243] op_sel_hi:[1,0]
	v_pk_mul_f32 v[206:207], v[6:7], v[242:243] op_sel_hi:[1,0]
	v_exp_f32_e32 v4, v4
	v_exp_f32_e32 v5, v5
	v_exp_f32_e32 v6, v6
	v_exp_f32_e32 v7, v7
	v_pk_fma_f32 v[208:209], v[204:205], v[244:245], v[238:239] op_sel_hi:[1,0,0]
	v_pk_fma_f32 v[210:211], v[206:207], v[244:245], v[238:239] op_sel_hi:[1,0,0]
	v_pk_fma_f32 v[208:209], v[204:205], v[208:209], v[246:247] op_sel_hi:[1,1,0]
	v_pk_fma_f32 v[210:211], v[206:207], v[210:211], v[246:247] op_sel_hi:[1,1,0]
	v_pk_fma_f32 v[208:209], v[204:205], v[208:209], v[248:249] op_sel_hi:[1,1,0]
	v_pk_fma_f32 v[210:211], v[206:207], v[210:211], v[248:249] op_sel_hi:[1,1,0]
	v_pk_fma_f32 v[208:209], v[204:205], v[208:209], v[240:241] op_sel_hi:[1,1,0]
	v_pk_fma_f32 v[210:211], v[206:207], v[210:211], v[240:241] op_sel_hi:[1,1,0]
	v_pk_mul_f32 v[208:209], v[208:209], v[204:205] neg_lo:[0,1] neg_hi:[0,1]
	v_pk_mul_f32 v[210:211], v[210:211], v[206:207] neg_lo:[0,1] neg_hi:[0,1]
	v_pk_fma_f32 v[212:213], v[4:5], v[4:5], v[240:241] op_sel_hi:[1,1,0] neg_lo:[1,0,0] neg_hi:[1,0,0]
	v_pk_fma_f32 v[214:215], v[6:7], v[6:7], v[240:241] op_sel_hi:[1,1,0] neg_lo:[1,0,0] neg_hi:[1,0,0]
	v_cmp_lt_f32_e64 s[70:71], s29, v204
	v_cmp_lt_f32_e64 s[72:73], s29, v205
	v_cmp_lt_f32_e64 s[74:75], s29, v206
	v_cmp_lt_f32_e64 s[76:77], s29, v207
	v_cndmask_b32_e64 v212, v212, v208, s[70:71]
	v_cndmask_b32_e64 v213, v213, v209, s[72:73]
	v_cndmask_b32_e64 v214, v214, v210, s[74:75]
	v_cndmask_b32_e64 v215, v215, v211, s[76:77]
	v_sqrt_f32_e32 v212, v212
	v_sqrt_f32_e32 v213, v213
	v_sqrt_f32_e32 v214, v214
	v_sqrt_f32_e32 v215, v215
	v_pk_mul_f32 v[12:13], v[200:201], v[212:213]
	v_pk_mul_f32 v[14:15], v[202:203], v[214:215]
	s_nop 1
	v_fmac_f32_dpp v12, v12, v4 row_shr:1 row_mask:0xf bank_mask:0xf
	v_fmac_f32_dpp v13, v13, v5 row_shr:1 row_mask:0xf bank_mask:0xf
	v_fmac_f32_dpp v14, v14, v6 row_shr:1 row_mask:0xf bank_mask:0xf
	v_fmac_f32_dpp v15, v15, v7 row_shr:1 row_mask:0xf bank_mask:0xf
	v_mul_f32_dpp v4, v4, v4 row_shr:1 row_mask:0xf bank_mask:0xf
	v_mul_f32_dpp v5, v5, v5 row_shr:1 row_mask:0xf bank_mask:0xf
	v_mul_f32_dpp v6, v6, v6 row_shr:1 row_mask:0xf bank_mask:0xf
	v_mul_f32_dpp v7, v7, v7 row_shr:1 row_mask:0xf bank_mask:0xf
	v_fmac_f32_dpp v12, v12, v4 row_shr:2 row_mask:0xf bank_mask:0xf
	v_fmac_f32_dpp v13, v13, v5 row_shr:2 row_mask:0xf bank_mask:0xf
	v_fmac_f32_dpp v14, v14, v6 row_shr:2 row_mask:0xf bank_mask:0xf
	v_fmac_f32_dpp v15, v15, v7 row_shr:2 row_mask:0xf bank_mask:0xf
	v_mul_f32_dpp v4, v4, v4 row_shr:2 row_mask:0xf bank_mask:0xf
	v_mul_f32_dpp v5, v5, v5 row_shr:2 row_mask:0xf bank_mask:0xf
	v_mul_f32_dpp v6, v6, v6 row_shr:2 row_mask:0xf bank_mask:0xf
	v_mul_f32_dpp v7, v7, v7 row_shr:2 row_mask:0xf bank_mask:0xf
	v_fmac_f32_dpp v12, v12, v4 row_shr:4 row_mask:0xf bank_mask:0xf
	v_fmac_f32_dpp v13, v13, v5 row_shr:4 row_mask:0xf bank_mask:0xf
	v_fmac_f32_dpp v14, v14, v6 row_shr:4 row_mask:0xf bank_mask:0xf
	v_fmac_f32_dpp v15, v15, v7 row_shr:4 row_mask:0xf bank_mask:0xf
	v_mul_f32_dpp v4, v4, v4 row_shr:4 row_mask:0xf bank_mask:0xf
	v_mul_f32_dpp v5, v5, v5 row_shr:4 row_mask:0xf bank_mask:0xf
	v_mul_f32_dpp v6, v6, v6 row_shr:4 row_mask:0xf bank_mask:0xf
	v_mul_f32_dpp v7, v7, v7 row_shr:4 row_mask:0xf bank_mask:0xf
	v_fmac_f32_dpp v12, v12, v4 row_shr:8 row_mask:0xf bank_mask:0xf
	v_fmac_f32_dpp v13, v13, v5 row_shr:8 row_mask:0xf bank_mask:0xf
	v_fmac_f32_dpp v14, v14, v6 row_shr:8 row_mask:0xf bank_mask:0xf
	v_fmac_f32_dpp v15, v15, v7 row_shr:8 row_mask:0xf bank_mask:0xf
	v_mul_f32_dpp v4, v4, v4 row_shr:8 row_mask:0xf bank_mask:0xf
	v_mul_f32_dpp v5, v5, v5 row_shr:8 row_mask:0xf bank_mask:0xf
	v_mul_f32_dpp v6, v6, v6 row_shr:8 row_mask:0xf bank_mask:0xf
	v_mul_f32_dpp v7, v7, v7 row_shr:8 row_mask:0xf bank_mask:0xf
	v_fmac_f32_dpp v12, v12, v4 row_bcast:15 row_mask:0xa bank_mask:0xf
	v_fmac_f32_dpp v13, v13, v5 row_bcast:15 row_mask:0xa bank_mask:0xf
	v_fmac_f32_dpp v14, v14, v6 row_bcast:15 row_mask:0xa bank_mask:0xf
	v_fmac_f32_dpp v15, v15, v7 row_bcast:15 row_mask:0xa bank_mask:0xf
	v_mul_f32_dpp v4, v4, v4 row_bcast:15 row_mask:0xa bank_mask:0xf
	v_mul_f32_dpp v5, v5, v5 row_bcast:15 row_mask:0xa bank_mask:0xf
	v_mul_f32_dpp v6, v6, v6 row_bcast:15 row_mask:0xa bank_mask:0xf
	v_mul_f32_dpp v7, v7, v7 row_bcast:15 row_mask:0xa bank_mask:0xf

; #define LAS __attribute__((address_space(3)))
; __device__ __forceinline__ void lru_phase(const Ptrs& P, LAS unsigned char* lds, int G, int wave, int lane, int tid) {
;     ...
;         v2u graw_[10];
;         { const bf16* gp = U0 + (size_t)M * LW + ((size_t)(((b * 128 + (tloc >> 5)) * 16 + hd) * 10) * 64 + lane) * 4;
; #pragma unroll
;           for (int gq = 0; gq < 10; ++gq) graw_[gq] = *(const v2u*)(gp + gq * 256); }
;         if (r == 31) { LAS float* cp = (LAS float*)(lds + L_COMP) + wave * 160 + 4 * hh;
; #pragma unroll
;             for (int s = 0; s < 5; ++s)
; #pragma unroll
;                 for (int half = 0; half < 2; ++half) { const int ch0 = 16 * s + 8 * half;
;                     *(LAS f32x4*)(cp + ch0) = (f32x4){Av[s][half][0], Av[s][half][1], Av[s][half][2], Av[s][half][3]};
;                     *(LAS f32x4*)(cp + 80 + ch0) = (f32x4){xc[s][half][0], xc[s][half][1], xc[s][half][2], xc[s][half][3]}; } }
	s_lshl_b32 s6, s31, 11
	s_lshr_b32 s7, s34, 1
	s_and_b32 s37, s20, 15
	s_add_i32 s7, s7, s6
	s_or_b32 s6, s7, s37
	s_mul_i32 s6, s6, 10
	s_ashr_i32 s7, s6, 31
	s_lshl_b64 s[6:7], s[6:7], 9
	v_lshl_add_u64 v[16:17], v[130:131], 0, s[6:7]
	global_load_dwordx2 v[200:201], v[16:17], off
	global_load_dwordx2 v[196:197], v[16:17], off offset:512
	global_load_dwordx2 v[194:195], v[16:17], off offset:1024
	global_load_dwordx2 v[192:193], v[16:17], off offset:1536
	global_load_dwordx2 v[190:191], v[16:17], off offset:2048
	global_load_dwordx2 v[188:189], v[16:17], off offset:2560
	global_load_dwordx2 v[182:183], v[16:17], off offset:3072
	global_load_dwordx2 v[180:181], v[16:17], off offset:3584
	v_add_co_u32_e32 v16, vcc, 0x1000, v16
	s_nop 1
	v_addc_co_u32_e32 v17, vcc, 0, v17, vcc
	global_load_dwordx2 v[178:179], v[16:17], off
	global_load_dwordx2 v[176:177], v[16:17], off offset:512
	s_and_saveexec_b64 s[6:7], s[2:3]
	s_cbranch_execz .LBB0_310
	v_add_u32_e32 v16, s27, v233
	ds_write_b128 v16, v[44:47] offset:39424
	ds_write_b128 v16, v[48:51] offset:39744
	ds_write_b128 v16, v[52:55] offset:39456
	ds_write_b128 v16, v[56:59] offset:39776
	ds_write_b128 v16, v[60:63] offset:39488
	ds_write_b128 v16, v[64:67] offset:39808
	ds_write_b128 v16, v[68:71] offset:39520
	ds_write_b128 v16, v[72:75] offset:39840
	ds_write_b128 v16, v[80:83] offset:39552
	ds_write_b128 v16, v[84:87] offset:39872
	ds_write_b128 v16, v[88:91] offset:39584
	ds_write_b128 v16, v[92:95] offset:39904
	ds_write_b128 v16, v[96:99] offset:39616
	ds_write_b128 v16, v[100:103] offset:39936
	ds_write_b128 v16, v[104:107] offset:39648
	ds_write_b128 v16, v[108:111] offset:39968
	ds_write_b128 v16, v[0:3] offset:39680
	ds_write_b128 v16, v[8:11] offset:40000
	ds_write_b128 v16, v[4:7] offset:39712
	ds_write_b128 v16, v[12:15] offset:40032
